# GEMM MFMA clusters: the redundant mid-cluster s_setprio 0 / s_setprio 1 pair removed (32 sites)
# speedup vs baseline: 1.0032x; 1.0032x over previous
.LBB0_211:
	ds_read_b128 v[154:157], v149
	ds_read_b128 v[158:161], v149 offset:1024
	ds_read_b128 v[162:165], v149 offset:2048
	ds_read_b128 v[166:169], v149 offset:3072
	ds_read_b128 v[170:173], v150
	ds_read_b128 v[174:177], v150 offset:1024
	ds_read_b128 v[178:181], v150 offset:2048
	ds_read_b128 v[182:185], v150 offset:3072
	s_add_u32 s48, s46, 0x100
	s_addc_u32 s49, s47, 0
	s_cmp_eq_u32 s79, 28
	s_cselect_b32 s59, s13, s49
	s_cselect_b32 s58, s75, s48
	s_cselect_b32 s57, s11, s78
	s_cselect_b32 s56, s76, s77
	v_lshl_add_u64 v[190:191], s[46:47], 0, v[138:139]
	s_add_i32 m0, s42, 0xc000
	ds_read_b128 v[186:189], v151
	ds_read_b128 v[194:197], v151 offset:1024
	ds_read_b128 v[198:201], v151 offset:2048
	ds_read_b128 v[202:205], v151 offset:3072
	ds_read_b128 v[206:209], v151 offset:4096
	ds_read_b128 v[210:213], v151 offset:5120
	ds_read_b128 v[214:217], v151 offset:6144
	ds_read_b128 v[218:221], v151 offset:7168
	global_load_lds_dwordx4 v[190:191], off
	v_lshl_add_u64 v[190:191], s[46:47], 0, v[140:141]
	s_add_i32 m0, s42, 0xe000
	s_nop 0
	global_load_lds_dwordx4 v[190:191], off
	s_waitcnt vmcnt(8)
	s_waitcnt lgkmcnt(0)
	s_barrier
	s_setprio 1
	s_waitcnt lgkmcnt(0)
	v_mfma_f32_16x16x32_bf16 v[124:127], v[154:157], v[186:189], v[124:127]
	v_mfma_f32_16x16x32_bf16 v[120:123], v[162:165], v[186:189], v[120:123]
	v_mfma_f32_16x16x32_bf16 v[112:115], v[154:157], v[198:201], v[112:115]
	v_mfma_f32_16x16x32_bf16 v[104:107], v[162:165], v[198:201], v[104:107]
	v_mfma_f32_16x16x32_bf16 v[100:103], v[154:157], v[206:209], v[100:103]
	v_mfma_f32_16x16x32_bf16 v[92:95], v[162:165], v[206:209], v[92:95]
	v_mfma_f32_16x16x32_bf16 v[84:87], v[154:157], v[214:217], v[84:87]
	v_mfma_f32_16x16x32_bf16 v[76:79], v[162:165], v[214:217], v[76:79]
	v_mfma_f32_16x16x32_bf16 v[124:127], v[158:161], v[194:197], v[124:127]
	v_mfma_f32_16x16x32_bf16 v[120:123], v[166:169], v[194:197], v[120:123]
	v_mfma_f32_16x16x32_bf16 v[112:115], v[158:161], v[202:205], v[112:115]
	v_mfma_f32_16x16x32_bf16 v[104:107], v[166:169], v[202:205], v[104:107]
	v_mfma_f32_16x16x32_bf16 v[100:103], v[158:161], v[210:213], v[100:103]
	v_mfma_f32_16x16x32_bf16 v[92:95], v[166:169], v[210:213], v[92:95]
	v_mfma_f32_16x16x32_bf16 v[84:87], v[158:161], v[218:221], v[84:87]
	v_mfma_f32_16x16x32_bf16 v[76:79], v[166:169], v[218:221], v[76:79]
	v_mfma_f32_16x16x32_bf16 v[116:119], v[170:173], v[186:189], v[116:119]
	v_mfma_f32_16x16x32_bf16 v[108:111], v[178:181], v[186:189], v[108:111]
	v_mfma_f32_16x16x32_bf16 v[96:99], v[170:173], v[198:201], v[96:99]
	v_mfma_f32_16x16x32_bf16 v[88:91], v[178:181], v[198:201], v[88:91]
	v_mfma_f32_16x16x32_bf16 v[80:83], v[170:173], v[206:209], v[80:83]
	v_mfma_f32_16x16x32_bf16 v[72:75], v[178:181], v[206:209], v[72:75]
	v_mfma_f32_16x16x32_bf16 v[68:71], v[170:173], v[214:217], v[68:71]
	v_mfma_f32_16x16x32_bf16 v[64:67], v[178:181], v[214:217], v[64:67]
	v_mfma_f32_16x16x32_bf16 v[116:119], v[174:177], v[194:197], v[116:119]
	v_mfma_f32_16x16x32_bf16 v[108:111], v[182:185], v[194:197], v[108:111]
	v_mfma_f32_16x16x32_bf16 v[96:99], v[174:177], v[202:205], v[96:99]
	v_mfma_f32_16x16x32_bf16 v[88:91], v[182:185], v[202:205], v[88:91]
	v_mfma_f32_16x16x32_bf16 v[80:83], v[174:177], v[210:213], v[80:83]
	v_mfma_f32_16x16x32_bf16 v[72:75], v[182:185], v[210:213], v[72:75]
	v_mfma_f32_16x16x32_bf16 v[68:71], v[174:177], v[218:221], v[68:71]
	v_mfma_f32_16x16x32_bf16 v[64:67], v[182:185], v[218:221], v[64:67]
	s_setprio 0
	s_barrier
	s_add_i32 s46, s73, s88
	v_lshl_add_u64 v[190:191], s[56:57], 0, v[132:133]
	s_mov_b32 m0, s46
	ds_read_b128 v[186:189], v151 offset:16384
	ds_read_b128 v[194:197], v151 offset:17408
	ds_read_b128 v[198:201], v151 offset:18432
	ds_read_b128 v[202:205], v151 offset:19456
	ds_read_b128 v[206:209], v151 offset:20480
	ds_read_b128 v[210:213], v151 offset:21504
	ds_read_b128 v[214:217], v151 offset:22528
	ds_read_b128 v[218:221], v151 offset:23552
	global_load_lds_dwordx4 v[190:191], off
	s_add_i32 m0, s46, 0x2000
	s_add_u32 s46, s56, 0x80000
	v_lshl_add_u64 v[222:223], s[56:57], 0, v[128:129]
	s_addc_u32 s47, s57, 0
	s_add_i32 s80, s74, s88
	global_load_lds_dwordx4 v[222:223], off
	v_lshl_add_u64 v[224:225], s[46:47], 0, v[132:133]
	s_mov_b32 m0, s80
	v_lshl_add_u64 v[226:227], s[58:59], 0, v[130:131]
	global_load_lds_dwordx4 v[224:225], off
	v_lshl_add_u64 v[224:225], s[46:47], 0, v[128:129]
	s_add_i32 m0, s80, 0x2000
	s_nop 0
	global_load_lds_dwordx4 v[224:225], off
	v_lshl_add_u64 v[224:225], s[58:59], 0, v[134:135]
	s_mov_b32 m0, s42
	s_nop 0
	global_load_lds_dwordx4 v[224:225], off
	s_mov_b32 m0, s43
	s_nop 0
	global_load_lds_dwordx4 v[226:227], off
	s_waitcnt vmcnt(8)
	s_waitcnt lgkmcnt(0)
	s_barrier
	s_setprio 1
	s_waitcnt lgkmcnt(0)
	v_mfma_f32_16x16x32_bf16 v[60:63], v[154:157], v[186:189], v[60:63]
	v_mfma_f32_16x16x32_bf16 v[56:59], v[162:165], v[186:189], v[56:59]
	v_mfma_f32_16x16x32_bf16 v[52:55], v[154:157], v[198:201], v[52:55]
	v_mfma_f32_16x16x32_bf16 v[44:47], v[162:165], v[198:201], v[44:47]
	v_mfma_f32_16x16x32_bf16 v[36:39], v[154:157], v[206:209], v[36:39]
	v_mfma_f32_16x16x32_bf16 v[28:31], v[162:165], v[206:209], v[28:31]
	v_mfma_f32_16x16x32_bf16 v[20:23], v[154:157], v[214:217], v[20:23]
	v_mfma_f32_16x16x32_bf16 v[12:15], v[162:165], v[214:217], v[12:15]
	v_mfma_f32_16x16x32_bf16 v[60:63], v[158:161], v[194:197], v[60:63]
	v_mfma_f32_16x16x32_bf16 v[56:59], v[166:169], v[194:197], v[56:59]
	v_mfma_f32_16x16x32_bf16 v[52:55], v[158:161], v[202:205], v[52:55]
	v_mfma_f32_16x16x32_bf16 v[44:47], v[166:169], v[202:205], v[44:47]
	v_mfma_f32_16x16x32_bf16 v[36:39], v[158:161], v[210:213], v[36:39]
	v_mfma_f32_16x16x32_bf16 v[28:31], v[166:169], v[210:213], v[28:31]
	v_mfma_f32_16x16x32_bf16 v[20:23], v[158:161], v[218:221], v[20:23]
	v_mfma_f32_16x16x32_bf16 v[12:15], v[166:169], v[218:221], v[12:15]
	v_mfma_f32_16x16x32_bf16 v[48:51], v[170:173], v[186:189], v[48:51]
	v_mfma_f32_16x16x32_bf16 v[40:43], v[178:181], v[186:189], v[40:43]
	v_mfma_f32_16x16x32_bf16 v[32:35], v[170:173], v[198:201], v[32:35]
	v_mfma_f32_16x16x32_bf16 v[24:27], v[178:181], v[198:201], v[24:27]
	v_mfma_f32_16x16x32_bf16 v[16:19], v[170:173], v[206:209], v[16:19]
	v_mfma_f32_16x16x32_bf16 v[8:11], v[178:181], v[206:209], v[8:11]
	v_mfma_f32_16x16x32_bf16 v[4:7], v[170:173], v[214:217], v[4:7]
	v_mfma_f32_16x16x32_bf16 v[0:3], v[178:181], v[214:217], v[0:3]
	v_mfma_f32_16x16x32_bf16 v[48:51], v[174:177], v[194:197], v[48:51]
	v_mfma_f32_16x16x32_bf16 v[40:43], v[182:185], v[194:197], v[40:43]
	v_mfma_f32_16x16x32_bf16 v[32:35], v[174:177], v[202:205], v[32:35]
	v_mfma_f32_16x16x32_bf16 v[24:27], v[182:185], v[202:205], v[24:27]
	v_mfma_f32_16x16x32_bf16 v[16:19], v[174:177], v[210:213], v[16:19]
	v_mfma_f32_16x16x32_bf16 v[8:11], v[182:185], v[210:213], v[8:11]
	v_mfma_f32_16x16x32_bf16 v[4:7], v[174:177], v[218:221], v[4:7]
	v_mfma_f32_16x16x32_bf16 v[0:3], v[182:185], v[218:221], v[0:3]
	s_setprio 0
	s_barrier
	s_add_i32 s80, 0, 0x18000
	v_add_u32_e32 v136, s80, v148
	s_add_i32 s81, 0, 0x1c000
	ds_read_b128 v[154:157], v136
	ds_read_b128 v[158:161], v136 offset:1024
	ds_read_b128 v[162:165], v136 offset:2048
	ds_read_b128 v[166:169], v136 offset:3072
	v_add_u32_e32 v136, s81, v148
	ds_read_b128 v[170:173], v136
	ds_read_b128 v[174:177], v136 offset:1024
	ds_read_b128 v[178:181], v136 offset:2048
	ds_read_b128 v[182:185], v136 offset:3072
	s_add_u32 s46, s58, 0x80000
	s_addc_u32 s47, s59, 0
	s_mov_b32 m0, s44
	v_lshl_add_u64 v[228:229], s[46:47], 0, v[134:135]
	ds_read_b128 v[186:189], v151 offset:32768
	ds_read_b128 v[194:197], v151 offset:33792
	ds_read_b128 v[198:201], v151 offset:34816
	ds_read_b128 v[202:205], v151 offset:35840
	ds_read_b128 v[206:209], v151 offset:36864
	ds_read_b128 v[210:213], v151 offset:37888
	ds_read_b128 v[214:217], v151 offset:38912
	ds_read_b128 v[218:221], v151 offset:39936
	global_load_lds_dwordx4 v[228:229], off
	v_lshl_add_u64 v[228:229], s[46:47], 0, v[130:131]
	s_mov_b32 m0, s45
	s_nop 0
	global_load_lds_dwordx4 v[228:229], off
	s_waitcnt vmcnt(8)
	s_waitcnt lgkmcnt(0)
	s_barrier
	s_setprio 1
	s_waitcnt lgkmcnt(0)
	v_mfma_f32_16x16x32_bf16 v[124:127], v[154:157], v[186:189], v[124:127]
	v_mfma_f32_16x16x32_bf16 v[120:123], v[162:165], v[186:189], v[120:123]
	v_mfma_f32_16x16x32_bf16 v[112:115], v[154:157], v[198:201], v[112:115]
	v_mfma_f32_16x16x32_bf16 v[104:107], v[162:165], v[198:201], v[104:107]
	v_mfma_f32_16x16x32_bf16 v[100:103], v[154:157], v[206:209], v[100:103]
	v_mfma_f32_16x16x32_bf16 v[92:95], v[162:165], v[206:209], v[92:95]
	v_mfma_f32_16x16x32_bf16 v[84:87], v[154:157], v[214:217], v[84:87]
	v_mfma_f32_16x16x32_bf16 v[76:79], v[162:165], v[214:217], v[76:79]
	v_mfma_f32_16x16x32_bf16 v[124:127], v[158:161], v[194:197], v[124:127]
	v_mfma_f32_16x16x32_bf16 v[120:123], v[166:169], v[194:197], v[120:123]
	v_mfma_f32_16x16x32_bf16 v[112:115], v[158:161], v[202:205], v[112:115]
	v_mfma_f32_16x16x32_bf16 v[104:107], v[166:169], v[202:205], v[104:107]
	v_mfma_f32_16x16x32_bf16 v[100:103], v[158:161], v[210:213], v[100:103]
	v_mfma_f32_16x16x32_bf16 v[92:95], v[166:169], v[210:213], v[92:95]
	v_mfma_f32_16x16x32_bf16 v[84:87], v[158:161], v[218:221], v[84:87]
	v_mfma_f32_16x16x32_bf16 v[76:79], v[166:169], v[218:221], v[76:79]
	v_mfma_f32_16x16x32_bf16 v[116:119], v[170:173], v[186:189], v[116:119]
	v_mfma_f32_16x16x32_bf16 v[108:111], v[178:181], v[186:189], v[108:111]
	v_mfma_f32_16x16x32_bf16 v[96:99], v[170:173], v[198:201], v[96:99]
	v_mfma_f32_16x16x32_bf16 v[88:91], v[178:181], v[198:201], v[88:91]
	v_mfma_f32_16x16x32_bf16 v[80:83], v[170:173], v[206:209], v[80:83]
	v_mfma_f32_16x16x32_bf16 v[72:75], v[178:181], v[206:209], v[72:75]
	v_mfma_f32_16x16x32_bf16 v[68:71], v[170:173], v[214:217], v[68:71]
	v_mfma_f32_16x16x32_bf16 v[64:67], v[178:181], v[214:217], v[64:67]
	v_mfma_f32_16x16x32_bf16 v[116:119], v[174:177], v[194:197], v[116:119]
	v_mfma_f32_16x16x32_bf16 v[108:111], v[182:185], v[194:197], v[108:111]
	v_mfma_f32_16x16x32_bf16 v[96:99], v[174:177], v[202:205], v[96:99]
	v_mfma_f32_16x16x32_bf16 v[88:91], v[182:185], v[202:205], v[88:91]
	v_mfma_f32_16x16x32_bf16 v[80:83], v[174:177], v[210:213], v[80:83]
	v_mfma_f32_16x16x32_bf16 v[72:75], v[182:185], v[210:213], v[72:75]
	v_mfma_f32_16x16x32_bf16 v[68:71], v[174:177], v[218:221], v[68:71]
	v_mfma_f32_16x16x32_bf16 v[64:67], v[182:185], v[218:221], v[64:67]
	s_setprio 0
	s_barrier
	s_add_i32 s46, s80, s88
	v_lshl_add_u64 v[190:191], v[190:191], 0, s[8:9]
	s_mov_b32 m0, s46
	ds_read_b128 v[186:189], v151 offset:49152
	ds_read_b128 v[194:197], v151 offset:50176
	ds_read_b128 v[198:201], v151 offset:51200
	ds_read_b128 v[202:205], v151 offset:52224
	ds_read_b128 v[206:209], v151 offset:53248
	ds_read_b128 v[210:213], v151 offset:54272
	ds_read_b128 v[214:217], v151 offset:55296
	ds_read_b128 v[218:221], v151 offset:56320
	global_load_lds_dwordx4 v[190:191], off
	s_add_i32 m0, s46, 0x2000
	s_add_u32 s46, s56, 0x80080
	v_lshl_add_u64 v[190:191], v[222:223], 0, s[8:9]
	s_addc_u32 s47, s57, 0
	s_add_i32 s56, s81, s88
	global_load_lds_dwordx4 v[190:191], off
	v_lshl_add_u64 v[190:191], s[46:47], 0, v[132:133]
	s_mov_b32 m0, s56
	s_nop 0
	global_load_lds_dwordx4 v[190:191], off
	v_lshl_add_u64 v[190:191], s[46:47], 0, v[128:129]
	s_add_i32 m0, s56, 0x2000
	s_nop 0
	global_load_lds_dwordx4 v[190:191], off
	v_lshl_add_u64 v[190:191], v[224:225], 0, s[8:9]
	s_mov_b32 m0, s69
	s_nop 0
	global_load_lds_dwordx4 v[190:191], off
	v_lshl_add_u64 v[190:191], v[226:227], 0, s[8:9]
	s_mov_b32 m0, s70
	s_nop 0
	global_load_lds_dwordx4 v[190:191], off
	s_waitcnt vmcnt(8)
	s_waitcnt lgkmcnt(0)
	s_barrier
	s_setprio 1
	s_waitcnt lgkmcnt(0)
	v_mfma_f32_16x16x32_bf16 v[60:63], v[154:157], v[186:189], v[60:63]
	v_mfma_f32_16x16x32_bf16 v[56:59], v[162:165], v[186:189], v[56:59]
	v_mfma_f32_16x16x32_bf16 v[52:55], v[154:157], v[198:201], v[52:55]
	v_mfma_f32_16x16x32_bf16 v[44:47], v[162:165], v[198:201], v[44:47]
	v_mfma_f32_16x16x32_bf16 v[36:39], v[154:157], v[206:209], v[36:39]
	v_mfma_f32_16x16x32_bf16 v[28:31], v[162:165], v[206:209], v[28:31]
	v_mfma_f32_16x16x32_bf16 v[20:23], v[154:157], v[214:217], v[20:23]
	v_mfma_f32_16x16x32_bf16 v[12:15], v[162:165], v[214:217], v[12:15]
	v_mfma_f32_16x16x32_bf16 v[60:63], v[158:161], v[194:197], v[60:63]
	v_mfma_f32_16x16x32_bf16 v[56:59], v[166:169], v[194:197], v[56:59]
	v_mfma_f32_16x16x32_bf16 v[52:55], v[158:161], v[202:205], v[52:55]
	v_mfma_f32_16x16x32_bf16 v[44:47], v[166:169], v[202:205], v[44:47]
	v_mfma_f32_16x16x32_bf16 v[36:39], v[158:161], v[210:213], v[36:39]
	v_mfma_f32_16x16x32_bf16 v[28:31], v[166:169], v[210:213], v[28:31]
	v_mfma_f32_16x16x32_bf16 v[20:23], v[158:161], v[218:221], v[20:23]
	v_mfma_f32_16x16x32_bf16 v[12:15], v[166:169], v[218:221], v[12:15]
	v_mfma_f32_16x16x32_bf16 v[48:51], v[170:173], v[186:189], v[48:51]
	v_mfma_f32_16x16x32_bf16 v[40:43], v[178:181], v[186:189], v[40:43]
	v_mfma_f32_16x16x32_bf16 v[32:35], v[170:173], v[198:201], v[32:35]
	v_mfma_f32_16x16x32_bf16 v[24:27], v[178:181], v[198:201], v[24:27]
	v_mfma_f32_16x16x32_bf16 v[16:19], v[170:173], v[206:209], v[16:19]
	v_mfma_f32_16x16x32_bf16 v[8:11], v[178:181], v[206:209], v[8:11]
	v_mfma_f32_16x16x32_bf16 v[4:7], v[170:173], v[214:217], v[4:7]
	v_mfma_f32_16x16x32_bf16 v[0:3], v[178:181], v[214:217], v[0:3]
	v_mfma_f32_16x16x32_bf16 v[48:51], v[174:177], v[194:197], v[48:51]
	v_mfma_f32_16x16x32_bf16 v[40:43], v[182:185], v[194:197], v[40:43]
	v_mfma_f32_16x16x32_bf16 v[32:35], v[174:177], v[202:205], v[32:35]
	v_mfma_f32_16x16x32_bf16 v[24:27], v[182:185], v[202:205], v[24:27]
	v_mfma_f32_16x16x32_bf16 v[16:19], v[174:177], v[210:213], v[16:19]
	v_mfma_f32_16x16x32_bf16 v[8:11], v[182:185], v[210:213], v[8:11]
	v_mfma_f32_16x16x32_bf16 v[4:7], v[174:177], v[218:221], v[4:7]
	v_mfma_f32_16x16x32_bf16 v[0:3], v[182:185], v[218:221], v[0:3]
	s_setprio 0
	s_barrier
	s_add_i32 s79, s79, 2
	s_add_u32 s77, s77, 0x100
	s_addc_u32 s78, s78, 0
	s_cmp_gt_u32 s79, 29
	s_mov_b64 s[46:47], s[48:49]
	s_cbranch_scc0 .LBB0_211
	s_and_b64 vcc, exec, s[0:1]
	s_cbranch_vccz .LBB0_214
	s_barrier

.LBB0_640:
	ds_read_b128 v[144:147], v153
	ds_read_b128 v[160:163], v153 offset:1024
	ds_read_b128 v[164:167], v153 offset:2048
	ds_read_b128 v[168:171], v153 offset:3072
	ds_read_b128 v[172:175], v154
	ds_read_b128 v[180:183], v154 offset:1024
	ds_read_b128 v[184:187], v154 offset:2048
	ds_read_b128 v[188:191], v154 offset:3072
	s_add_u32 s64, s62, 0x100
	s_addc_u32 s65, s63, 0
	s_cmp_eq_u32 s78, 28
	s_cselect_b32 s71, s49, s65
	s_cselect_b32 s70, s59, s64
	s_cselect_b32 s67, s47, s77
	s_cselect_b32 s66, s75, s76
	v_lshl_add_u64 v[148:149], s[62:63], 0, v[136:137]
	s_add_i32 m0, s21, 0xc000
	ds_read_b128 v[192:195], v155
	ds_read_b128 v[196:199], v155 offset:1024
	ds_read_b128 v[200:203], v155 offset:2048
	ds_read_b128 v[204:207], v155 offset:3072
	ds_read_b128 v[208:211], v155 offset:4096
	ds_read_b128 v[212:215], v155 offset:5120
	ds_read_b128 v[216:219], v155 offset:6144
	ds_read_b128 v[220:223], v155 offset:7168
	global_load_lds_dwordx4 v[148:149], off
	v_lshl_add_u64 v[148:149], s[62:63], 0, v[138:139]
	s_add_i32 m0, s21, 0xe000
	s_nop 0
	global_load_lds_dwordx4 v[148:149], off
	s_waitcnt vmcnt(8)
	s_waitcnt lgkmcnt(0)
	s_barrier
	s_setprio 1
	s_waitcnt lgkmcnt(0)
	v_mfma_f32_16x16x32_bf16 v[124:127], v[144:147], v[192:195], v[124:127]
	v_mfma_f32_16x16x32_bf16 v[120:123], v[164:167], v[192:195], v[120:123]
	v_mfma_f32_16x16x32_bf16 v[108:111], v[144:147], v[200:203], v[108:111]
	v_mfma_f32_16x16x32_bf16 v[104:107], v[164:167], v[200:203], v[104:107]
	v_mfma_f32_16x16x32_bf16 v[92:95], v[144:147], v[208:211], v[92:95]
	v_mfma_f32_16x16x32_bf16 v[88:91], v[164:167], v[208:211], v[88:91]
	v_mfma_f32_16x16x32_bf16 v[76:79], v[144:147], v[216:219], v[76:79]
	v_mfma_f32_16x16x32_bf16 v[72:75], v[164:167], v[216:219], v[72:75]
	v_mfma_f32_16x16x32_bf16 v[124:127], v[160:163], v[196:199], v[124:127]
	v_mfma_f32_16x16x32_bf16 v[120:123], v[168:171], v[196:199], v[120:123]
	v_mfma_f32_16x16x32_bf16 v[108:111], v[160:163], v[204:207], v[108:111]
	v_mfma_f32_16x16x32_bf16 v[104:107], v[168:171], v[204:207], v[104:107]
	v_mfma_f32_16x16x32_bf16 v[92:95], v[160:163], v[212:215], v[92:95]
	v_mfma_f32_16x16x32_bf16 v[88:91], v[168:171], v[212:215], v[88:91]
	v_mfma_f32_16x16x32_bf16 v[76:79], v[160:163], v[220:223], v[76:79]
	v_mfma_f32_16x16x32_bf16 v[72:75], v[168:171], v[220:223], v[72:75]
	v_mfma_f32_16x16x32_bf16 v[116:119], v[172:175], v[192:195], v[116:119]
	v_mfma_f32_16x16x32_bf16 v[112:115], v[184:187], v[192:195], v[112:115]
	v_mfma_f32_16x16x32_bf16 v[100:103], v[172:175], v[200:203], v[100:103]
	v_mfma_f32_16x16x32_bf16 v[96:99], v[184:187], v[200:203], v[96:99]
	v_mfma_f32_16x16x32_bf16 v[84:87], v[172:175], v[208:211], v[84:87]
	v_mfma_f32_16x16x32_bf16 v[80:83], v[184:187], v[208:211], v[80:83]
	v_mfma_f32_16x16x32_bf16 v[68:71], v[172:175], v[216:219], v[68:71]
	v_mfma_f32_16x16x32_bf16 v[64:67], v[184:187], v[216:219], v[64:67]
	v_mfma_f32_16x16x32_bf16 v[116:119], v[180:183], v[196:199], v[116:119]
	v_mfma_f32_16x16x32_bf16 v[112:115], v[188:191], v[196:199], v[112:115]
	v_mfma_f32_16x16x32_bf16 v[100:103], v[180:183], v[204:207], v[100:103]
	v_mfma_f32_16x16x32_bf16 v[96:99], v[188:191], v[204:207], v[96:99]
	v_mfma_f32_16x16x32_bf16 v[84:87], v[180:183], v[212:215], v[84:87]
	v_mfma_f32_16x16x32_bf16 v[80:83], v[188:191], v[212:215], v[80:83]
	v_mfma_f32_16x16x32_bf16 v[68:71], v[180:183], v[220:223], v[68:71]
	v_mfma_f32_16x16x32_bf16 v[64:67], v[188:191], v[220:223], v[64:67]
	s_setprio 0
	s_barrier
	s_add_i32 s62, s44, s88
	v_lshl_add_u64 v[148:149], s[66:67], 0, v[130:131]
	s_mov_b32 m0, s62
	ds_read_b128 v[192:195], v155 offset:16384
	ds_read_b128 v[196:199], v155 offset:17408
	ds_read_b128 v[200:203], v155 offset:18432
	ds_read_b128 v[204:207], v155 offset:19456
	ds_read_b128 v[208:211], v155 offset:20480
	ds_read_b128 v[212:215], v155 offset:21504
	ds_read_b128 v[216:219], v155 offset:22528
	ds_read_b128 v[220:223], v155 offset:23552
	global_load_lds_dwordx4 v[148:149], off
	s_add_i32 m0, s62, 0x2000
	s_add_u32 s62, s66, 0x80000
	v_lshl_add_u64 v[224:225], s[66:67], 0, v[134:135]
	s_addc_u32 s63, s67, 0
	s_add_i32 s79, s45, s88
	global_load_lds_dwordx4 v[224:225], off
	v_lshl_add_u64 v[226:227], s[62:63], 0, v[130:131]
	s_mov_b32 m0, s79
	v_lshl_add_u64 v[228:229], s[70:71], 0, v[132:133]
	global_load_lds_dwordx4 v[226:227], off
	v_lshl_add_u64 v[226:227], s[62:63], 0, v[134:135]
	s_add_i32 m0, s79, 0x2000
	s_nop 0
	global_load_lds_dwordx4 v[226:227], off
	v_lshl_add_u64 v[226:227], s[70:71], 0, v[128:129]
	s_mov_b32 m0, s21
	s_nop 0
	global_load_lds_dwordx4 v[226:227], off
	s_mov_b32 m0, s23
	s_nop 0
	global_load_lds_dwordx4 v[228:229], off
	s_waitcnt vmcnt(8)
	s_waitcnt lgkmcnt(0)
	s_barrier
	s_setprio 1
	s_waitcnt lgkmcnt(0)
	v_mfma_f32_16x16x32_bf16 v[60:63], v[144:147], v[192:195], v[60:63]
	v_mfma_f32_16x16x32_bf16 v[56:59], v[164:167], v[192:195], v[56:59]
	v_mfma_f32_16x16x32_bf16 v[44:47], v[144:147], v[200:203], v[44:47]
	v_mfma_f32_16x16x32_bf16 v[40:43], v[164:167], v[200:203], v[40:43]
	v_mfma_f32_16x16x32_bf16 v[28:31], v[144:147], v[208:211], v[28:31]
	v_mfma_f32_16x16x32_bf16 v[24:27], v[164:167], v[208:211], v[24:27]
	v_mfma_f32_16x16x32_bf16 v[12:15], v[144:147], v[216:219], v[12:15]
	v_mfma_f32_16x16x32_bf16 v[8:11], v[164:167], v[216:219], v[8:11]
	v_mfma_f32_16x16x32_bf16 v[60:63], v[160:163], v[196:199], v[60:63]
	v_mfma_f32_16x16x32_bf16 v[56:59], v[168:171], v[196:199], v[56:59]
	v_mfma_f32_16x16x32_bf16 v[44:47], v[160:163], v[204:207], v[44:47]
	v_mfma_f32_16x16x32_bf16 v[40:43], v[168:171], v[204:207], v[40:43]
	v_mfma_f32_16x16x32_bf16 v[28:31], v[160:163], v[212:215], v[28:31]
	v_mfma_f32_16x16x32_bf16 v[24:27], v[168:171], v[212:215], v[24:27]
	v_mfma_f32_16x16x32_bf16 v[12:15], v[160:163], v[220:223], v[12:15]
	v_mfma_f32_16x16x32_bf16 v[8:11], v[168:171], v[220:223], v[8:11]
	v_mfma_f32_16x16x32_bf16 v[52:55], v[172:175], v[192:195], v[52:55]
	v_mfma_f32_16x16x32_bf16 v[48:51], v[184:187], v[192:195], v[48:51]
	v_mfma_f32_16x16x32_bf16 v[36:39], v[172:175], v[200:203], v[36:39]
	v_mfma_f32_16x16x32_bf16 v[32:35], v[184:187], v[200:203], v[32:35]
	v_mfma_f32_16x16x32_bf16 v[20:23], v[172:175], v[208:211], v[20:23]
	v_mfma_f32_16x16x32_bf16 v[16:19], v[184:187], v[208:211], v[16:19]
	v_mfma_f32_16x16x32_bf16 v[4:7], v[172:175], v[216:219], v[4:7]
	v_mfma_f32_16x16x32_bf16 v[0:3], v[184:187], v[216:219], v[0:3]
	v_mfma_f32_16x16x32_bf16 v[52:55], v[180:183], v[196:199], v[52:55]
	v_mfma_f32_16x16x32_bf16 v[48:51], v[188:191], v[196:199], v[48:51]
	v_mfma_f32_16x16x32_bf16 v[36:39], v[180:183], v[204:207], v[36:39]
	v_mfma_f32_16x16x32_bf16 v[32:35], v[188:191], v[204:207], v[32:35]
	v_mfma_f32_16x16x32_bf16 v[20:23], v[180:183], v[212:215], v[20:23]
	v_mfma_f32_16x16x32_bf16 v[16:19], v[188:191], v[212:215], v[16:19]
	v_mfma_f32_16x16x32_bf16 v[4:7], v[180:183], v[220:223], v[4:7]
	v_mfma_f32_16x16x32_bf16 v[0:3], v[188:191], v[220:223], v[0:3]
	s_setprio 0
	s_barrier
	s_add_i32 s79, 0, 0x18000
	v_add_u32_e32 v159, s79, v150
	s_add_i32 s80, 0, 0x1c000
	ds_read_b128 v[144:147], v159
	ds_read_b128 v[160:163], v159 offset:1024
	ds_read_b128 v[164:167], v159 offset:2048
	ds_read_b128 v[168:171], v159 offset:3072
	v_add_u32_e32 v159, s80, v150
	ds_read_b128 v[172:175], v159
	ds_read_b128 v[180:183], v159 offset:1024
	ds_read_b128 v[184:187], v159 offset:2048
	ds_read_b128 v[188:191], v159 offset:3072
	s_add_u32 s62, s70, 0x80000
	s_addc_u32 s63, s71, 0
	s_mov_b32 m0, s42
	v_lshl_add_u64 v[230:231], s[62:63], 0, v[128:129]
	ds_read_b128 v[192:195], v155 offset:32768
	ds_read_b128 v[196:199], v155 offset:33792
	ds_read_b128 v[200:203], v155 offset:34816
	ds_read_b128 v[204:207], v155 offset:35840
	ds_read_b128 v[208:211], v155 offset:36864
	ds_read_b128 v[212:215], v155 offset:37888
	ds_read_b128 v[216:219], v155 offset:38912
	ds_read_b128 v[220:223], v155 offset:39936
	global_load_lds_dwordx4 v[230:231], off
	v_lshl_add_u64 v[230:231], s[62:63], 0, v[132:133]
	s_mov_b32 m0, s43
	s_nop 0
	global_load_lds_dwordx4 v[230:231], off
	s_waitcnt vmcnt(8)
	s_waitcnt lgkmcnt(0)
	s_barrier
	s_setprio 1
	s_waitcnt lgkmcnt(0)
	v_mfma_f32_16x16x32_bf16 v[124:127], v[144:147], v[192:195], v[124:127]
	v_mfma_f32_16x16x32_bf16 v[120:123], v[164:167], v[192:195], v[120:123]
	v_mfma_f32_16x16x32_bf16 v[108:111], v[144:147], v[200:203], v[108:111]
	v_mfma_f32_16x16x32_bf16 v[104:107], v[164:167], v[200:203], v[104:107]
	v_mfma_f32_16x16x32_bf16 v[92:95], v[144:147], v[208:211], v[92:95]
	v_mfma_f32_16x16x32_bf16 v[88:91], v[164:167], v[208:211], v[88:91]
	v_mfma_f32_16x16x32_bf16 v[76:79], v[144:147], v[216:219], v[76:79]
	v_mfma_f32_16x16x32_bf16 v[72:75], v[164:167], v[216:219], v[72:75]
	v_mfma_f32_16x16x32_bf16 v[124:127], v[160:163], v[196:199], v[124:127]
	v_mfma_f32_16x16x32_bf16 v[120:123], v[168:171], v[196:199], v[120:123]
	v_mfma_f32_16x16x32_bf16 v[108:111], v[160:163], v[204:207], v[108:111]
	v_mfma_f32_16x16x32_bf16 v[104:107], v[168:171], v[204:207], v[104:107]
	v_mfma_f32_16x16x32_bf16 v[92:95], v[160:163], v[212:215], v[92:95]
	v_mfma_f32_16x16x32_bf16 v[88:91], v[168:171], v[212:215], v[88:91]
	v_mfma_f32_16x16x32_bf16 v[76:79], v[160:163], v[220:223], v[76:79]
	v_mfma_f32_16x16x32_bf16 v[72:75], v[168:171], v[220:223], v[72:75]
	v_mfma_f32_16x16x32_bf16 v[116:119], v[172:175], v[192:195], v[116:119]
	v_mfma_f32_16x16x32_bf16 v[112:115], v[184:187], v[192:195], v[112:115]
	v_mfma_f32_16x16x32_bf16 v[100:103], v[172:175], v[200:203], v[100:103]
	v_mfma_f32_16x16x32_bf16 v[96:99], v[184:187], v[200:203], v[96:99]
	v_mfma_f32_16x16x32_bf16 v[84:87], v[172:175], v[208:211], v[84:87]
	v_mfma_f32_16x16x32_bf16 v[80:83], v[184:187], v[208:211], v[80:83]
	v_mfma_f32_16x16x32_bf16 v[68:71], v[172:175], v[216:219], v[68:71]
	v_mfma_f32_16x16x32_bf16 v[64:67], v[184:187], v[216:219], v[64:67]
	v_mfma_f32_16x16x32_bf16 v[116:119], v[180:183], v[196:199], v[116:119]
	v_mfma_f32_16x16x32_bf16 v[112:115], v[188:191], v[196:199], v[112:115]
	v_mfma_f32_16x16x32_bf16 v[100:103], v[180:183], v[204:207], v[100:103]
	v_mfma_f32_16x16x32_bf16 v[96:99], v[188:191], v[204:207], v[96:99]
	v_mfma_f32_16x16x32_bf16 v[84:87], v[180:183], v[212:215], v[84:87]
	v_mfma_f32_16x16x32_bf16 v[80:83], v[188:191], v[212:215], v[80:83]
	v_mfma_f32_16x16x32_bf16 v[68:71], v[180:183], v[220:223], v[68:71]
	v_mfma_f32_16x16x32_bf16 v[64:67], v[188:191], v[220:223], v[64:67]
	s_setprio 0
	s_barrier
	s_add_i32 s62, s79, s88
	v_lshl_add_u64 v[148:149], v[148:149], 0, s[36:37]
	s_mov_b32 m0, s62
	ds_read_b128 v[192:195], v155 offset:49152
	ds_read_b128 v[196:199], v155 offset:50176
	ds_read_b128 v[200:203], v155 offset:51200
	ds_read_b128 v[204:207], v155 offset:52224
	ds_read_b128 v[208:211], v155 offset:53248
	ds_read_b128 v[212:215], v155 offset:54272
	ds_read_b128 v[216:219], v155 offset:55296
	ds_read_b128 v[220:223], v155 offset:56320
	global_load_lds_dwordx4 v[148:149], off
	s_add_i32 m0, s62, 0x2000
	s_add_u32 s62, s66, 0x80080
	v_lshl_add_u64 v[148:149], v[224:225], 0, s[36:37]
	s_addc_u32 s63, s67, 0
	s_add_i32 s66, s80, s88
	global_load_lds_dwordx4 v[148:149], off
	v_lshl_add_u64 v[148:149], s[62:63], 0, v[130:131]
	s_mov_b32 m0, s66
	s_nop 0
	global_load_lds_dwordx4 v[148:149], off
	v_lshl_add_u64 v[148:149], s[62:63], 0, v[134:135]
	s_add_i32 m0, s66, 0x2000
	s_nop 0
	global_load_lds_dwordx4 v[148:149], off
	v_lshl_add_u64 v[148:149], v[226:227], 0, s[36:37]
	s_mov_b32 m0, s68
	s_nop 0
	global_load_lds_dwordx4 v[148:149], off
	v_lshl_add_u64 v[148:149], v[228:229], 0, s[36:37]
	s_mov_b32 m0, s69
	s_nop 0
	global_load_lds_dwordx4 v[148:149], off
	s_waitcnt vmcnt(8)
	s_waitcnt lgkmcnt(0)
	s_barrier
	s_setprio 1
	s_waitcnt lgkmcnt(0)
	v_mfma_f32_16x16x32_bf16 v[60:63], v[144:147], v[192:195], v[60:63]
	v_mfma_f32_16x16x32_bf16 v[56:59], v[164:167], v[192:195], v[56:59]
	v_mfma_f32_16x16x32_bf16 v[44:47], v[144:147], v[200:203], v[44:47]
	v_mfma_f32_16x16x32_bf16 v[40:43], v[164:167], v[200:203], v[40:43]
	v_mfma_f32_16x16x32_bf16 v[28:31], v[144:147], v[208:211], v[28:31]
	v_mfma_f32_16x16x32_bf16 v[24:27], v[164:167], v[208:211], v[24:27]
	v_mfma_f32_16x16x32_bf16 v[12:15], v[144:147], v[216:219], v[12:15]
	v_mfma_f32_16x16x32_bf16 v[8:11], v[164:167], v[216:219], v[8:11]
	v_mfma_f32_16x16x32_bf16 v[60:63], v[160:163], v[196:199], v[60:63]
	v_mfma_f32_16x16x32_bf16 v[56:59], v[168:171], v[196:199], v[56:59]
	v_mfma_f32_16x16x32_bf16 v[44:47], v[160:163], v[204:207], v[44:47]
	v_mfma_f32_16x16x32_bf16 v[40:43], v[168:171], v[204:207], v[40:43]
	v_mfma_f32_16x16x32_bf16 v[28:31], v[160:163], v[212:215], v[28:31]
	v_mfma_f32_16x16x32_bf16 v[24:27], v[168:171], v[212:215], v[24:27]
	v_mfma_f32_16x16x32_bf16 v[12:15], v[160:163], v[220:223], v[12:15]
	v_mfma_f32_16x16x32_bf16 v[8:11], v[168:171], v[220:223], v[8:11]
	v_mfma_f32_16x16x32_bf16 v[52:55], v[172:175], v[192:195], v[52:55]
	v_mfma_f32_16x16x32_bf16 v[48:51], v[184:187], v[192:195], v[48:51]
	v_mfma_f32_16x16x32_bf16 v[36:39], v[172:175], v[200:203], v[36:39]
	v_mfma_f32_16x16x32_bf16 v[32:35], v[184:187], v[200:203], v[32:35]
	v_mfma_f32_16x16x32_bf16 v[20:23], v[172:175], v[208:211], v[20:23]
	v_mfma_f32_16x16x32_bf16 v[16:19], v[184:187], v[208:211], v[16:19]
	v_mfma_f32_16x16x32_bf16 v[4:7], v[172:175], v[216:219], v[4:7]
	v_mfma_f32_16x16x32_bf16 v[0:3], v[184:187], v[216:219], v[0:3]
	v_mfma_f32_16x16x32_bf16 v[52:55], v[180:183], v[196:199], v[52:55]
	v_mfma_f32_16x16x32_bf16 v[48:51], v[188:191], v[196:199], v[48:51]
	v_mfma_f32_16x16x32_bf16 v[36:39], v[180:183], v[204:207], v[36:39]
	v_mfma_f32_16x16x32_bf16 v[32:35], v[188:191], v[204:207], v[32:35]
	v_mfma_f32_16x16x32_bf16 v[20:23], v[180:183], v[212:215], v[20:23]
	v_mfma_f32_16x16x32_bf16 v[16:19], v[188:191], v[212:215], v[16:19]
	v_mfma_f32_16x16x32_bf16 v[4:7], v[180:183], v[220:223], v[4:7]
	v_mfma_f32_16x16x32_bf16 v[0:3], v[188:191], v[220:223], v[0:3]
	s_setprio 0
	s_barrier
	s_add_i32 s78, s78, 2
	s_add_u32 s76, s76, 0x100
	s_addc_u32 s77, s77, 0
	s_cmp_gt_u32 s78, 29
	s_mov_b64 s[62:63], s[64:65]
	s_cbranch_scc0 .LBB0_640
	s_and_b64 vcc, exec, s[10:11]
	s_cbranch_vccz .LBB0_643
	s_barrier

.LBB0_732:
	ds_read_b128 v[144:147], v151
	ds_read_b128 v[160:163], v151 offset:1024
	ds_read_b128 v[164:167], v151 offset:2048
	ds_read_b128 v[168:171], v151 offset:3072
	ds_read_b128 v[172:175], v152
	ds_read_b128 v[180:183], v152 offset:1024
	ds_read_b128 v[184:187], v152 offset:2048
	ds_read_b128 v[188:191], v152 offset:3072
	s_add_u32 s58, s56, 0x100
	s_addc_u32 s59, s57, 0
	s_cmp_eq_u32 s73, 28
	s_cselect_b32 s63, s44, s59
	s_cselect_b32 s62, s45, s58
	s_cselect_b32 s61, s47, s72
	s_cselect_b32 s60, s49, s71
	v_lshl_add_u64 v[224:225], s[56:57], 0, v[136:137]
	s_add_i32 m0, s23, 0xc000
	ds_read_b128 v[192:195], v153
	ds_read_b128 v[196:199], v153 offset:1024
	ds_read_b128 v[200:203], v153 offset:2048
	ds_read_b128 v[204:207], v153 offset:3072
	ds_read_b128 v[208:211], v153 offset:4096
	ds_read_b128 v[212:215], v153 offset:5120
	ds_read_b128 v[216:219], v153 offset:6144
	ds_read_b128 v[220:223], v153 offset:7168
	global_load_lds_dwordx4 v[224:225], off
	v_lshl_add_u64 v[224:225], s[56:57], 0, v[138:139]
	s_add_i32 m0, s23, 0xe000
	s_nop 0
	global_load_lds_dwordx4 v[224:225], off
	s_waitcnt vmcnt(8)
	s_waitcnt lgkmcnt(0)
	s_barrier
	s_setprio 1
	s_waitcnt lgkmcnt(0)
	v_mfma_f32_16x16x32_bf16 v[124:127], v[144:147], v[192:195], v[124:127]
	v_mfma_f32_16x16x32_bf16 v[120:123], v[164:167], v[192:195], v[120:123]
	v_mfma_f32_16x16x32_bf16 v[108:111], v[144:147], v[200:203], v[108:111]
	v_mfma_f32_16x16x32_bf16 v[104:107], v[164:167], v[200:203], v[104:107]
	v_mfma_f32_16x16x32_bf16 v[92:95], v[144:147], v[208:211], v[92:95]
	v_mfma_f32_16x16x32_bf16 v[88:91], v[164:167], v[208:211], v[88:91]
	v_mfma_f32_16x16x32_bf16 v[76:79], v[144:147], v[216:219], v[76:79]
	v_mfma_f32_16x16x32_bf16 v[72:75], v[164:167], v[216:219], v[72:75]
	v_mfma_f32_16x16x32_bf16 v[124:127], v[160:163], v[196:199], v[124:127]
	v_mfma_f32_16x16x32_bf16 v[120:123], v[168:171], v[196:199], v[120:123]
	v_mfma_f32_16x16x32_bf16 v[108:111], v[160:163], v[204:207], v[108:111]
	v_mfma_f32_16x16x32_bf16 v[104:107], v[168:171], v[204:207], v[104:107]
	v_mfma_f32_16x16x32_bf16 v[92:95], v[160:163], v[212:215], v[92:95]
	v_mfma_f32_16x16x32_bf16 v[88:91], v[168:171], v[212:215], v[88:91]
	v_mfma_f32_16x16x32_bf16 v[76:79], v[160:163], v[220:223], v[76:79]
	v_mfma_f32_16x16x32_bf16 v[72:75], v[168:171], v[220:223], v[72:75]
	v_mfma_f32_16x16x32_bf16 v[116:119], v[172:175], v[192:195], v[116:119]
	v_mfma_f32_16x16x32_bf16 v[112:115], v[184:187], v[192:195], v[112:115]
	v_mfma_f32_16x16x32_bf16 v[100:103], v[172:175], v[200:203], v[100:103]
	v_mfma_f32_16x16x32_bf16 v[96:99], v[184:187], v[200:203], v[96:99]
	v_mfma_f32_16x16x32_bf16 v[84:87], v[172:175], v[208:211], v[84:87]
	v_mfma_f32_16x16x32_bf16 v[80:83], v[184:187], v[208:211], v[80:83]
	v_mfma_f32_16x16x32_bf16 v[68:71], v[172:175], v[216:219], v[68:71]
	v_mfma_f32_16x16x32_bf16 v[64:67], v[184:187], v[216:219], v[64:67]
	v_mfma_f32_16x16x32_bf16 v[116:119], v[180:183], v[196:199], v[116:119]
	v_mfma_f32_16x16x32_bf16 v[112:115], v[188:191], v[196:199], v[112:115]
	v_mfma_f32_16x16x32_bf16 v[100:103], v[180:183], v[204:207], v[100:103]
	v_mfma_f32_16x16x32_bf16 v[96:99], v[188:191], v[204:207], v[96:99]
	v_mfma_f32_16x16x32_bf16 v[84:87], v[180:183], v[212:215], v[84:87]
	v_mfma_f32_16x16x32_bf16 v[80:83], v[188:191], v[212:215], v[80:83]
	v_mfma_f32_16x16x32_bf16 v[68:71], v[180:183], v[220:223], v[68:71]
	v_mfma_f32_16x16x32_bf16 v[64:67], v[188:191], v[220:223], v[64:67]
	s_setprio 0
	s_barrier
	s_add_i32 s56, s68, s88
	v_lshl_add_u64 v[224:225], s[60:61], 0, v[130:131]
	s_mov_b32 m0, s56
	ds_read_b128 v[192:195], v153 offset:16384
	ds_read_b128 v[196:199], v153 offset:17408
	ds_read_b128 v[200:203], v153 offset:18432
	ds_read_b128 v[204:207], v153 offset:19456
	ds_read_b128 v[208:211], v153 offset:20480
	ds_read_b128 v[212:215], v153 offset:21504
	ds_read_b128 v[216:219], v153 offset:22528
	ds_read_b128 v[220:223], v153 offset:23552
	global_load_lds_dwordx4 v[224:225], off
	s_add_i32 m0, s56, 0x2000
	s_add_u32 s56, s60, 0x80000
	v_lshl_add_u64 v[226:227], s[60:61], 0, v[134:135]
	s_addc_u32 s57, s61, 0
	s_add_i32 s74, s69, s88
	global_load_lds_dwordx4 v[226:227], off
	v_lshl_add_u64 v[228:229], s[56:57], 0, v[130:131]
	s_mov_b32 m0, s74
	v_lshl_add_u64 v[230:231], s[62:63], 0, v[132:133]
	global_load_lds_dwordx4 v[228:229], off
	v_lshl_add_u64 v[228:229], s[56:57], 0, v[134:135]
	s_add_i32 m0, s74, 0x2000
	s_nop 0
	global_load_lds_dwordx4 v[228:229], off
	v_lshl_add_u64 v[228:229], s[62:63], 0, v[128:129]
	s_mov_b32 m0, s23
	s_nop 0
	global_load_lds_dwordx4 v[228:229], off
	s_mov_b32 m0, s36
	s_nop 0
	global_load_lds_dwordx4 v[230:231], off
	s_waitcnt vmcnt(8)
	s_waitcnt lgkmcnt(0)
	s_barrier
	s_setprio 1
	s_waitcnt lgkmcnt(0)
	v_mfma_f32_16x16x32_bf16 v[60:63], v[144:147], v[192:195], v[60:63]
	v_mfma_f32_16x16x32_bf16 v[56:59], v[164:167], v[192:195], v[56:59]
	v_mfma_f32_16x16x32_bf16 v[44:47], v[144:147], v[200:203], v[44:47]
	v_mfma_f32_16x16x32_bf16 v[40:43], v[164:167], v[200:203], v[40:43]
	v_mfma_f32_16x16x32_bf16 v[28:31], v[144:147], v[208:211], v[28:31]
	v_mfma_f32_16x16x32_bf16 v[24:27], v[164:167], v[208:211], v[24:27]
	v_mfma_f32_16x16x32_bf16 v[12:15], v[144:147], v[216:219], v[12:15]
	v_mfma_f32_16x16x32_bf16 v[8:11], v[164:167], v[216:219], v[8:11]
	v_mfma_f32_16x16x32_bf16 v[60:63], v[160:163], v[196:199], v[60:63]
	v_mfma_f32_16x16x32_bf16 v[56:59], v[168:171], v[196:199], v[56:59]
	v_mfma_f32_16x16x32_bf16 v[44:47], v[160:163], v[204:207], v[44:47]
	v_mfma_f32_16x16x32_bf16 v[40:43], v[168:171], v[204:207], v[40:43]
	v_mfma_f32_16x16x32_bf16 v[28:31], v[160:163], v[212:215], v[28:31]
	v_mfma_f32_16x16x32_bf16 v[24:27], v[168:171], v[212:215], v[24:27]
	v_mfma_f32_16x16x32_bf16 v[12:15], v[160:163], v[220:223], v[12:15]
	v_mfma_f32_16x16x32_bf16 v[8:11], v[168:171], v[220:223], v[8:11]
	v_mfma_f32_16x16x32_bf16 v[52:55], v[172:175], v[192:195], v[52:55]
	v_mfma_f32_16x16x32_bf16 v[48:51], v[184:187], v[192:195], v[48:51]
	v_mfma_f32_16x16x32_bf16 v[36:39], v[172:175], v[200:203], v[36:39]
	v_mfma_f32_16x16x32_bf16 v[32:35], v[184:187], v[200:203], v[32:35]
	v_mfma_f32_16x16x32_bf16 v[20:23], v[172:175], v[208:211], v[20:23]
	v_mfma_f32_16x16x32_bf16 v[16:19], v[184:187], v[208:211], v[16:19]
	v_mfma_f32_16x16x32_bf16 v[4:7], v[172:175], v[216:219], v[4:7]
	v_mfma_f32_16x16x32_bf16 v[0:3], v[184:187], v[216:219], v[0:3]
	v_mfma_f32_16x16x32_bf16 v[52:55], v[180:183], v[196:199], v[52:55]
	v_mfma_f32_16x16x32_bf16 v[48:51], v[188:191], v[196:199], v[48:51]
	v_mfma_f32_16x16x32_bf16 v[36:39], v[180:183], v[204:207], v[36:39]
	v_mfma_f32_16x16x32_bf16 v[32:35], v[188:191], v[204:207], v[32:35]
	v_mfma_f32_16x16x32_bf16 v[20:23], v[180:183], v[212:215], v[20:23]
	v_mfma_f32_16x16x32_bf16 v[16:19], v[188:191], v[212:215], v[16:19]
	v_mfma_f32_16x16x32_bf16 v[4:7], v[180:183], v[220:223], v[4:7]
	v_mfma_f32_16x16x32_bf16 v[0:3], v[188:191], v[220:223], v[0:3]
	s_setprio 0
	s_barrier
	s_add_i32 s74, 0, 0x18000
	v_add_u32_e32 v159, s74, v148
	s_add_i32 s75, 0, 0x1c000
	ds_read_b128 v[144:147], v159
	ds_read_b128 v[160:163], v159 offset:1024
	ds_read_b128 v[164:167], v159 offset:2048
	ds_read_b128 v[168:171], v159 offset:3072
	v_add_u32_e32 v159, s75, v148
	ds_read_b128 v[172:175], v159
	ds_read_b128 v[180:183], v159 offset:1024
	ds_read_b128 v[184:187], v159 offset:2048
	ds_read_b128 v[188:191], v159 offset:3072
	s_add_u32 s56, s62, 0x80000
	s_addc_u32 s57, s63, 0
	s_mov_b32 m0, s37
	v_lshl_add_u64 v[232:233], s[56:57], 0, v[128:129]
	ds_read_b128 v[192:195], v153 offset:32768
	ds_read_b128 v[196:199], v153 offset:33792
	ds_read_b128 v[200:203], v153 offset:34816
	ds_read_b128 v[204:207], v153 offset:35840
	ds_read_b128 v[208:211], v153 offset:36864
	ds_read_b128 v[212:215], v153 offset:37888
	ds_read_b128 v[216:219], v153 offset:38912
	ds_read_b128 v[220:223], v153 offset:39936
	global_load_lds_dwordx4 v[232:233], off
	v_lshl_add_u64 v[232:233], s[56:57], 0, v[132:133]
	s_mov_b32 m0, s42
	s_nop 0
	global_load_lds_dwordx4 v[232:233], off
	s_waitcnt vmcnt(8)
	s_waitcnt lgkmcnt(0)
	s_barrier
	s_setprio 1
	s_waitcnt lgkmcnt(0)
	v_mfma_f32_16x16x32_bf16 v[124:127], v[144:147], v[192:195], v[124:127]
	v_mfma_f32_16x16x32_bf16 v[120:123], v[164:167], v[192:195], v[120:123]
	v_mfma_f32_16x16x32_bf16 v[108:111], v[144:147], v[200:203], v[108:111]
	v_mfma_f32_16x16x32_bf16 v[104:107], v[164:167], v[200:203], v[104:107]
	v_mfma_f32_16x16x32_bf16 v[92:95], v[144:147], v[208:211], v[92:95]
	v_mfma_f32_16x16x32_bf16 v[88:91], v[164:167], v[208:211], v[88:91]
	v_mfma_f32_16x16x32_bf16 v[76:79], v[144:147], v[216:219], v[76:79]
	v_mfma_f32_16x16x32_bf16 v[72:75], v[164:167], v[216:219], v[72:75]
	v_mfma_f32_16x16x32_bf16 v[124:127], v[160:163], v[196:199], v[124:127]
	v_mfma_f32_16x16x32_bf16 v[120:123], v[168:171], v[196:199], v[120:123]
	v_mfma_f32_16x16x32_bf16 v[108:111], v[160:163], v[204:207], v[108:111]
	v_mfma_f32_16x16x32_bf16 v[104:107], v[168:171], v[204:207], v[104:107]
	v_mfma_f32_16x16x32_bf16 v[92:95], v[160:163], v[212:215], v[92:95]
	v_mfma_f32_16x16x32_bf16 v[88:91], v[168:171], v[212:215], v[88:91]
	v_mfma_f32_16x16x32_bf16 v[76:79], v[160:163], v[220:223], v[76:79]
	v_mfma_f32_16x16x32_bf16 v[72:75], v[168:171], v[220:223], v[72:75]
	v_mfma_f32_16x16x32_bf16 v[116:119], v[172:175], v[192:195], v[116:119]
	v_mfma_f32_16x16x32_bf16 v[112:115], v[184:187], v[192:195], v[112:115]
	v_mfma_f32_16x16x32_bf16 v[100:103], v[172:175], v[200:203], v[100:103]
	v_mfma_f32_16x16x32_bf16 v[96:99], v[184:187], v[200:203], v[96:99]
	v_mfma_f32_16x16x32_bf16 v[84:87], v[172:175], v[208:211], v[84:87]
	v_mfma_f32_16x16x32_bf16 v[80:83], v[184:187], v[208:211], v[80:83]
	v_mfma_f32_16x16x32_bf16 v[68:71], v[172:175], v[216:219], v[68:71]
	v_mfma_f32_16x16x32_bf16 v[64:67], v[184:187], v[216:219], v[64:67]
	v_mfma_f32_16x16x32_bf16 v[116:119], v[180:183], v[196:199], v[116:119]
	v_mfma_f32_16x16x32_bf16 v[112:115], v[188:191], v[196:199], v[112:115]
	v_mfma_f32_16x16x32_bf16 v[100:103], v[180:183], v[204:207], v[100:103]
	v_mfma_f32_16x16x32_bf16 v[96:99], v[188:191], v[204:207], v[96:99]
	v_mfma_f32_16x16x32_bf16 v[84:87], v[180:183], v[212:215], v[84:87]
	v_mfma_f32_16x16x32_bf16 v[80:83], v[188:191], v[212:215], v[80:83]
	v_mfma_f32_16x16x32_bf16 v[68:71], v[180:183], v[220:223], v[68:71]
	v_mfma_f32_16x16x32_bf16 v[64:67], v[188:191], v[220:223], v[64:67]
	s_setprio 0
	s_barrier
	s_add_i32 s56, s74, s88
	v_lshl_add_u64 v[224:225], v[224:225], 0, s[16:17]
	s_mov_b32 m0, s56
	ds_read_b128 v[192:195], v153 offset:49152
	ds_read_b128 v[196:199], v153 offset:50176
	ds_read_b128 v[200:203], v153 offset:51200
	ds_read_b128 v[204:207], v153 offset:52224
	ds_read_b128 v[208:211], v153 offset:53248
	ds_read_b128 v[212:215], v153 offset:54272
	ds_read_b128 v[216:219], v153 offset:55296
	ds_read_b128 v[220:223], v153 offset:56320
	global_load_lds_dwordx4 v[224:225], off
	s_add_i32 m0, s56, 0x2000
	s_add_u32 s56, s60, 0x80080
	v_lshl_add_u64 v[224:225], v[226:227], 0, s[16:17]
	s_addc_u32 s57, s61, 0
	s_add_i32 s60, s75, s88
	global_load_lds_dwordx4 v[224:225], off
	v_lshl_add_u64 v[224:225], s[56:57], 0, v[130:131]
	s_mov_b32 m0, s60
	s_nop 0
	global_load_lds_dwordx4 v[224:225], off
	v_lshl_add_u64 v[224:225], s[56:57], 0, v[134:135]
	s_add_i32 m0, s60, 0x2000
	s_nop 0
	global_load_lds_dwordx4 v[224:225], off
	v_lshl_add_u64 v[224:225], v[228:229], 0, s[16:17]
	s_mov_b32 m0, s64
	s_nop 0
	global_load_lds_dwordx4 v[224:225], off
	v_lshl_add_u64 v[224:225], v[230:231], 0, s[16:17]
	s_mov_b32 m0, s65
	s_nop 0
	global_load_lds_dwordx4 v[224:225], off
	s_waitcnt vmcnt(8)
	s_waitcnt lgkmcnt(0)
	s_barrier
	s_setprio 1
	s_waitcnt lgkmcnt(0)
	v_mfma_f32_16x16x32_bf16 v[60:63], v[144:147], v[192:195], v[60:63]
	v_mfma_f32_16x16x32_bf16 v[56:59], v[164:167], v[192:195], v[56:59]
	v_mfma_f32_16x16x32_bf16 v[44:47], v[144:147], v[200:203], v[44:47]
	v_mfma_f32_16x16x32_bf16 v[40:43], v[164:167], v[200:203], v[40:43]
	v_mfma_f32_16x16x32_bf16 v[28:31], v[144:147], v[208:211], v[28:31]
	v_mfma_f32_16x16x32_bf16 v[24:27], v[164:167], v[208:211], v[24:27]
	v_mfma_f32_16x16x32_bf16 v[12:15], v[144:147], v[216:219], v[12:15]
	v_mfma_f32_16x16x32_bf16 v[8:11], v[164:167], v[216:219], v[8:11]
	v_mfma_f32_16x16x32_bf16 v[60:63], v[160:163], v[196:199], v[60:63]
	v_mfma_f32_16x16x32_bf16 v[56:59], v[168:171], v[196:199], v[56:59]
	v_mfma_f32_16x16x32_bf16 v[44:47], v[160:163], v[204:207], v[44:47]
	v_mfma_f32_16x16x32_bf16 v[40:43], v[168:171], v[204:207], v[40:43]
	v_mfma_f32_16x16x32_bf16 v[28:31], v[160:163], v[212:215], v[28:31]
	v_mfma_f32_16x16x32_bf16 v[24:27], v[168:171], v[212:215], v[24:27]
	v_mfma_f32_16x16x32_bf16 v[12:15], v[160:163], v[220:223], v[12:15]
	v_mfma_f32_16x16x32_bf16 v[8:11], v[168:171], v[220:223], v[8:11]
	v_mfma_f32_16x16x32_bf16 v[52:55], v[172:175], v[192:195], v[52:55]
	v_mfma_f32_16x16x32_bf16 v[48:51], v[184:187], v[192:195], v[48:51]
	v_mfma_f32_16x16x32_bf16 v[36:39], v[172:175], v[200:203], v[36:39]
	v_mfma_f32_16x16x32_bf16 v[32:35], v[184:187], v[200:203], v[32:35]
	v_mfma_f32_16x16x32_bf16 v[20:23], v[172:175], v[208:211], v[20:23]
	v_mfma_f32_16x16x32_bf16 v[16:19], v[184:187], v[208:211], v[16:19]
	v_mfma_f32_16x16x32_bf16 v[4:7], v[172:175], v[216:219], v[4:7]
	v_mfma_f32_16x16x32_bf16 v[0:3], v[184:187], v[216:219], v[0:3]
	v_mfma_f32_16x16x32_bf16 v[52:55], v[180:183], v[196:199], v[52:55]
	v_mfma_f32_16x16x32_bf16 v[48:51], v[188:191], v[196:199], v[48:51]
	v_mfma_f32_16x16x32_bf16 v[36:39], v[180:183], v[204:207], v[36:39]
	v_mfma_f32_16x16x32_bf16 v[32:35], v[188:191], v[204:207], v[32:35]
	v_mfma_f32_16x16x32_bf16 v[20:23], v[180:183], v[212:215], v[20:23]
	v_mfma_f32_16x16x32_bf16 v[16:19], v[188:191], v[212:215], v[16:19]
	v_mfma_f32_16x16x32_bf16 v[4:7], v[180:183], v[220:223], v[4:7]
	v_mfma_f32_16x16x32_bf16 v[0:3], v[188:191], v[220:223], v[0:3]
	s_setprio 0
	s_barrier
	s_add_i32 s73, s73, 2
	s_add_u32 s71, s71, 0x100
	s_addc_u32 s72, s72, 0
	s_cmp_gt_u32 s73, 29
	s_mov_b64 s[56:57], s[58:59]
	s_cbranch_scc0 .LBB0_732
	s_and_b64 vcc, exec, s[8:9]
	s_cbranch_vccz .LBB0_735
	s_barrier

.LBB0_810:
	ds_read_b128 v[144:147], v153
	ds_read_b128 v[160:163], v153 offset:1024
	ds_read_b128 v[164:167], v153 offset:2048
	ds_read_b128 v[168:171], v153 offset:3072
	ds_read_b128 v[172:175], v154
	ds_read_b128 v[180:183], v154 offset:1024
	ds_read_b128 v[184:187], v154 offset:2048
	ds_read_b128 v[188:191], v154 offset:3072
	s_add_u32 s66, s64, 0x100
	s_addc_u32 s67, s65, 0
	s_cmpk_eq_i32 s78, 0x7c
	s_cselect_b32 s73, s55, s67
	s_cselect_b32 s72, s61, s66
	s_cselect_b32 s71, s53, s77
	s_cselect_b32 s70, s75, s76
	v_lshl_add_u64 v[148:149], s[64:65], 0, v[136:137]
	s_add_i32 m0, s21, 0xc000
	ds_read_b128 v[192:195], v155
	ds_read_b128 v[196:199], v155 offset:1024
	ds_read_b128 v[200:203], v155 offset:2048
	ds_read_b128 v[204:207], v155 offset:3072
	ds_read_b128 v[208:211], v155 offset:4096
	ds_read_b128 v[212:215], v155 offset:5120
	ds_read_b128 v[216:219], v155 offset:6144
	ds_read_b128 v[220:223], v155 offset:7168
	global_load_lds_dwordx4 v[148:149], off
	v_lshl_add_u64 v[148:149], s[64:65], 0, v[138:139]
	s_add_i32 m0, s21, 0xe000
	s_nop 0
	global_load_lds_dwordx4 v[148:149], off
	s_waitcnt vmcnt(8)
	s_waitcnt lgkmcnt(0)
	s_barrier
	s_setprio 1
	s_waitcnt lgkmcnt(0)
	v_mfma_f32_16x16x32_bf16 v[124:127], v[144:147], v[192:195], v[124:127]
	v_mfma_f32_16x16x32_bf16 v[120:123], v[164:167], v[192:195], v[120:123]
	v_mfma_f32_16x16x32_bf16 v[108:111], v[144:147], v[200:203], v[108:111]
	v_mfma_f32_16x16x32_bf16 v[104:107], v[164:167], v[200:203], v[104:107]
	v_mfma_f32_16x16x32_bf16 v[92:95], v[144:147], v[208:211], v[92:95]
	v_mfma_f32_16x16x32_bf16 v[88:91], v[164:167], v[208:211], v[88:91]
	v_mfma_f32_16x16x32_bf16 v[76:79], v[144:147], v[216:219], v[76:79]
	v_mfma_f32_16x16x32_bf16 v[72:75], v[164:167], v[216:219], v[72:75]
	v_mfma_f32_16x16x32_bf16 v[124:127], v[160:163], v[196:199], v[124:127]
	v_mfma_f32_16x16x32_bf16 v[120:123], v[168:171], v[196:199], v[120:123]
	v_mfma_f32_16x16x32_bf16 v[108:111], v[160:163], v[204:207], v[108:111]
	v_mfma_f32_16x16x32_bf16 v[104:107], v[168:171], v[204:207], v[104:107]
	v_mfma_f32_16x16x32_bf16 v[92:95], v[160:163], v[212:215], v[92:95]
	v_mfma_f32_16x16x32_bf16 v[88:91], v[168:171], v[212:215], v[88:91]
	v_mfma_f32_16x16x32_bf16 v[76:79], v[160:163], v[220:223], v[76:79]
	v_mfma_f32_16x16x32_bf16 v[72:75], v[168:171], v[220:223], v[72:75]
	v_mfma_f32_16x16x32_bf16 v[116:119], v[172:175], v[192:195], v[116:119]
	v_mfma_f32_16x16x32_bf16 v[112:115], v[184:187], v[192:195], v[112:115]
	v_mfma_f32_16x16x32_bf16 v[100:103], v[172:175], v[200:203], v[100:103]
	v_mfma_f32_16x16x32_bf16 v[96:99], v[184:187], v[200:203], v[96:99]
	v_mfma_f32_16x16x32_bf16 v[84:87], v[172:175], v[208:211], v[84:87]
	v_mfma_f32_16x16x32_bf16 v[80:83], v[184:187], v[208:211], v[80:83]
	v_mfma_f32_16x16x32_bf16 v[68:71], v[172:175], v[216:219], v[68:71]
	v_mfma_f32_16x16x32_bf16 v[64:67], v[184:187], v[216:219], v[64:67]
	v_mfma_f32_16x16x32_bf16 v[116:119], v[180:183], v[196:199], v[116:119]
	v_mfma_f32_16x16x32_bf16 v[112:115], v[188:191], v[196:199], v[112:115]
	v_mfma_f32_16x16x32_bf16 v[100:103], v[180:183], v[204:207], v[100:103]
	v_mfma_f32_16x16x32_bf16 v[96:99], v[188:191], v[204:207], v[96:99]
	v_mfma_f32_16x16x32_bf16 v[84:87], v[180:183], v[212:215], v[84:87]
	v_mfma_f32_16x16x32_bf16 v[80:83], v[188:191], v[212:215], v[80:83]
	v_mfma_f32_16x16x32_bf16 v[68:71], v[180:183], v[220:223], v[68:71]
	v_mfma_f32_16x16x32_bf16 v[64:67], v[188:191], v[220:223], v[64:67]
	s_setprio 0
	s_barrier
	s_add_i32 s64, s44, s88
	v_lshl_add_u64 v[148:149], s[70:71], 0, v[130:131]
	s_mov_b32 m0, s64
	ds_read_b128 v[192:195], v155 offset:16384
	ds_read_b128 v[196:199], v155 offset:17408
	ds_read_b128 v[200:203], v155 offset:18432
	ds_read_b128 v[204:207], v155 offset:19456
	ds_read_b128 v[208:211], v155 offset:20480
	ds_read_b128 v[212:215], v155 offset:21504
	ds_read_b128 v[216:219], v155 offset:22528
	ds_read_b128 v[220:223], v155 offset:23552
	global_load_lds_dwordx4 v[148:149], off
	s_add_i32 m0, s64, 0x2000
	s_add_u32 s64, s70, 0x200000
	v_lshl_add_u64 v[224:225], s[70:71], 0, v[134:135]
	s_addc_u32 s65, s71, 0
	s_add_i32 s79, s45, s88
	global_load_lds_dwordx4 v[224:225], off
	v_lshl_add_u64 v[226:227], s[64:65], 0, v[130:131]
	s_mov_b32 m0, s79
	v_lshl_add_u64 v[228:229], s[72:73], 0, v[132:133]
	global_load_lds_dwordx4 v[226:227], off
	v_lshl_add_u64 v[226:227], s[64:65], 0, v[134:135]
	s_add_i32 m0, s79, 0x2000
	s_nop 0
	global_load_lds_dwordx4 v[226:227], off
	v_lshl_add_u64 v[226:227], s[72:73], 0, v[128:129]
	s_mov_b32 m0, s21
	s_nop 0
	global_load_lds_dwordx4 v[226:227], off
	s_mov_b32 m0, s23
	s_nop 0
	global_load_lds_dwordx4 v[228:229], off
	s_waitcnt vmcnt(8)
	s_waitcnt lgkmcnt(0)
	s_barrier
	s_setprio 1
	s_waitcnt lgkmcnt(0)
	v_mfma_f32_16x16x32_bf16 v[60:63], v[144:147], v[192:195], v[60:63]
	v_mfma_f32_16x16x32_bf16 v[56:59], v[164:167], v[192:195], v[56:59]
	v_mfma_f32_16x16x32_bf16 v[44:47], v[144:147], v[200:203], v[44:47]
	v_mfma_f32_16x16x32_bf16 v[40:43], v[164:167], v[200:203], v[40:43]
	v_mfma_f32_16x16x32_bf16 v[28:31], v[144:147], v[208:211], v[28:31]
	v_mfma_f32_16x16x32_bf16 v[24:27], v[164:167], v[208:211], v[24:27]
	v_mfma_f32_16x16x32_bf16 v[12:15], v[144:147], v[216:219], v[12:15]
	v_mfma_f32_16x16x32_bf16 v[8:11], v[164:167], v[216:219], v[8:11]
	v_mfma_f32_16x16x32_bf16 v[60:63], v[160:163], v[196:199], v[60:63]
	v_mfma_f32_16x16x32_bf16 v[56:59], v[168:171], v[196:199], v[56:59]
	v_mfma_f32_16x16x32_bf16 v[44:47], v[160:163], v[204:207], v[44:47]
	v_mfma_f32_16x16x32_bf16 v[40:43], v[168:171], v[204:207], v[40:43]
	v_mfma_f32_16x16x32_bf16 v[28:31], v[160:163], v[212:215], v[28:31]
	v_mfma_f32_16x16x32_bf16 v[24:27], v[168:171], v[212:215], v[24:27]
	v_mfma_f32_16x16x32_bf16 v[12:15], v[160:163], v[220:223], v[12:15]
	v_mfma_f32_16x16x32_bf16 v[8:11], v[168:171], v[220:223], v[8:11]
	v_mfma_f32_16x16x32_bf16 v[52:55], v[172:175], v[192:195], v[52:55]
	v_mfma_f32_16x16x32_bf16 v[48:51], v[184:187], v[192:195], v[48:51]
	v_mfma_f32_16x16x32_bf16 v[36:39], v[172:175], v[200:203], v[36:39]
	v_mfma_f32_16x16x32_bf16 v[32:35], v[184:187], v[200:203], v[32:35]
	v_mfma_f32_16x16x32_bf16 v[20:23], v[172:175], v[208:211], v[20:23]
	v_mfma_f32_16x16x32_bf16 v[16:19], v[184:187], v[208:211], v[16:19]
	v_mfma_f32_16x16x32_bf16 v[4:7], v[172:175], v[216:219], v[4:7]
	v_mfma_f32_16x16x32_bf16 v[0:3], v[184:187], v[216:219], v[0:3]
	v_mfma_f32_16x16x32_bf16 v[52:55], v[180:183], v[196:199], v[52:55]
	v_mfma_f32_16x16x32_bf16 v[48:51], v[188:191], v[196:199], v[48:51]
	v_mfma_f32_16x16x32_bf16 v[36:39], v[180:183], v[204:207], v[36:39]
	v_mfma_f32_16x16x32_bf16 v[32:35], v[188:191], v[204:207], v[32:35]
	v_mfma_f32_16x16x32_bf16 v[20:23], v[180:183], v[212:215], v[20:23]
	v_mfma_f32_16x16x32_bf16 v[16:19], v[188:191], v[212:215], v[16:19]
	v_mfma_f32_16x16x32_bf16 v[4:7], v[180:183], v[220:223], v[4:7]
	v_mfma_f32_16x16x32_bf16 v[0:3], v[188:191], v[220:223], v[0:3]
	s_setprio 0
	s_barrier
	s_add_i32 s79, 0, 0x18000
	v_add_u32_e32 v159, s79, v150
	s_add_i32 s80, 0, 0x1c000
	ds_read_b128 v[144:147], v159
	ds_read_b128 v[160:163], v159 offset:1024
	ds_read_b128 v[164:167], v159 offset:2048
	ds_read_b128 v[168:171], v159 offset:3072
	v_add_u32_e32 v159, s80, v150
	ds_read_b128 v[172:175], v159
	ds_read_b128 v[180:183], v159 offset:1024
	ds_read_b128 v[184:187], v159 offset:2048
	ds_read_b128 v[188:191], v159 offset:3072
	s_add_u32 s64, s72, 0x200000
	s_addc_u32 s65, s73, 0
	s_mov_b32 m0, s36
	v_lshl_add_u64 v[230:231], s[64:65], 0, v[128:129]
	ds_read_b128 v[192:195], v155 offset:32768
	ds_read_b128 v[196:199], v155 offset:33792
	ds_read_b128 v[200:203], v155 offset:34816
	ds_read_b128 v[204:207], v155 offset:35840
	ds_read_b128 v[208:211], v155 offset:36864
	ds_read_b128 v[212:215], v155 offset:37888
	ds_read_b128 v[216:219], v155 offset:38912
	ds_read_b128 v[220:223], v155 offset:39936
	global_load_lds_dwordx4 v[230:231], off
	v_lshl_add_u64 v[230:231], s[64:65], 0, v[132:133]
	s_mov_b32 m0, s37
	s_nop 0
	global_load_lds_dwordx4 v[230:231], off
	s_waitcnt vmcnt(8)
	s_waitcnt lgkmcnt(0)
	s_barrier
	s_setprio 1
	s_waitcnt lgkmcnt(0)
	v_mfma_f32_16x16x32_bf16 v[124:127], v[144:147], v[192:195], v[124:127]
	v_mfma_f32_16x16x32_bf16 v[120:123], v[164:167], v[192:195], v[120:123]
	v_mfma_f32_16x16x32_bf16 v[108:111], v[144:147], v[200:203], v[108:111]
	v_mfma_f32_16x16x32_bf16 v[104:107], v[164:167], v[200:203], v[104:107]
	v_mfma_f32_16x16x32_bf16 v[92:95], v[144:147], v[208:211], v[92:95]
	v_mfma_f32_16x16x32_bf16 v[88:91], v[164:167], v[208:211], v[88:91]
	v_mfma_f32_16x16x32_bf16 v[76:79], v[144:147], v[216:219], v[76:79]
	v_mfma_f32_16x16x32_bf16 v[72:75], v[164:167], v[216:219], v[72:75]
	v_mfma_f32_16x16x32_bf16 v[124:127], v[160:163], v[196:199], v[124:127]
	v_mfma_f32_16x16x32_bf16 v[120:123], v[168:171], v[196:199], v[120:123]
	v_mfma_f32_16x16x32_bf16 v[108:111], v[160:163], v[204:207], v[108:111]
	v_mfma_f32_16x16x32_bf16 v[104:107], v[168:171], v[204:207], v[104:107]
	v_mfma_f32_16x16x32_bf16 v[92:95], v[160:163], v[212:215], v[92:95]
	v_mfma_f32_16x16x32_bf16 v[88:91], v[168:171], v[212:215], v[88:91]
	v_mfma_f32_16x16x32_bf16 v[76:79], v[160:163], v[220:223], v[76:79]
	v_mfma_f32_16x16x32_bf16 v[72:75], v[168:171], v[220:223], v[72:75]
	v_mfma_f32_16x16x32_bf16 v[116:119], v[172:175], v[192:195], v[116:119]
	v_mfma_f32_16x16x32_bf16 v[112:115], v[184:187], v[192:195], v[112:115]
	v_mfma_f32_16x16x32_bf16 v[100:103], v[172:175], v[200:203], v[100:103]
	v_mfma_f32_16x16x32_bf16 v[96:99], v[184:187], v[200:203], v[96:99]
	v_mfma_f32_16x16x32_bf16 v[84:87], v[172:175], v[208:211], v[84:87]
	v_mfma_f32_16x16x32_bf16 v[80:83], v[184:187], v[208:211], v[80:83]
	v_mfma_f32_16x16x32_bf16 v[68:71], v[172:175], v[216:219], v[68:71]
	v_mfma_f32_16x16x32_bf16 v[64:67], v[184:187], v[216:219], v[64:67]
	v_mfma_f32_16x16x32_bf16 v[116:119], v[180:183], v[196:199], v[116:119]
	v_mfma_f32_16x16x32_bf16 v[112:115], v[188:191], v[196:199], v[112:115]
	v_mfma_f32_16x16x32_bf16 v[100:103], v[180:183], v[204:207], v[100:103]
	v_mfma_f32_16x16x32_bf16 v[96:99], v[188:191], v[204:207], v[96:99]
	v_mfma_f32_16x16x32_bf16 v[84:87], v[180:183], v[212:215], v[84:87]
	v_mfma_f32_16x16x32_bf16 v[80:83], v[188:191], v[212:215], v[80:83]
	v_mfma_f32_16x16x32_bf16 v[68:71], v[180:183], v[220:223], v[68:71]
	v_mfma_f32_16x16x32_bf16 v[64:67], v[188:191], v[220:223], v[64:67]
	s_setprio 0
	s_barrier
	s_add_i32 s64, s79, s88
	v_lshl_add_u64 v[148:149], v[148:149], 0, s[48:49]
	s_mov_b32 m0, s64
	ds_read_b128 v[192:195], v155 offset:49152
	ds_read_b128 v[196:199], v155 offset:50176
	ds_read_b128 v[200:203], v155 offset:51200
	ds_read_b128 v[204:207], v155 offset:52224
	ds_read_b128 v[208:211], v155 offset:53248
	ds_read_b128 v[212:215], v155 offset:54272
	ds_read_b128 v[216:219], v155 offset:55296
	ds_read_b128 v[220:223], v155 offset:56320
	global_load_lds_dwordx4 v[148:149], off
	s_add_i32 m0, s64, 0x2000
	s_add_u32 s64, s70, 0x200080
	v_lshl_add_u64 v[148:149], v[224:225], 0, s[48:49]
	s_addc_u32 s65, s71, 0
	s_add_i32 s70, s80, s88
	global_load_lds_dwordx4 v[148:149], off
	v_lshl_add_u64 v[148:149], s[64:65], 0, v[130:131]
	s_mov_b32 m0, s70
	s_nop 0
	global_load_lds_dwordx4 v[148:149], off
	v_lshl_add_u64 v[148:149], s[64:65], 0, v[134:135]
	s_add_i32 m0, s70, 0x2000
	s_nop 0
	global_load_lds_dwordx4 v[148:149], off
	v_lshl_add_u64 v[148:149], v[226:227], 0, s[48:49]
	s_mov_b32 m0, s43
	s_nop 0
	global_load_lds_dwordx4 v[148:149], off
	v_lshl_add_u64 v[148:149], v[228:229], 0, s[48:49]
	s_mov_b32 m0, s63
	s_nop 0
	global_load_lds_dwordx4 v[148:149], off
	s_waitcnt vmcnt(8)
	s_waitcnt lgkmcnt(0)
	s_barrier
	s_setprio 1
	s_waitcnt lgkmcnt(0)
	v_mfma_f32_16x16x32_bf16 v[60:63], v[144:147], v[192:195], v[60:63]
	v_mfma_f32_16x16x32_bf16 v[56:59], v[164:167], v[192:195], v[56:59]
	v_mfma_f32_16x16x32_bf16 v[44:47], v[144:147], v[200:203], v[44:47]
	v_mfma_f32_16x16x32_bf16 v[40:43], v[164:167], v[200:203], v[40:43]
	v_mfma_f32_16x16x32_bf16 v[28:31], v[144:147], v[208:211], v[28:31]
	v_mfma_f32_16x16x32_bf16 v[24:27], v[164:167], v[208:211], v[24:27]
	v_mfma_f32_16x16x32_bf16 v[12:15], v[144:147], v[216:219], v[12:15]
	v_mfma_f32_16x16x32_bf16 v[8:11], v[164:167], v[216:219], v[8:11]
	v_mfma_f32_16x16x32_bf16 v[60:63], v[160:163], v[196:199], v[60:63]
	v_mfma_f32_16x16x32_bf16 v[56:59], v[168:171], v[196:199], v[56:59]
	v_mfma_f32_16x16x32_bf16 v[44:47], v[160:163], v[204:207], v[44:47]
	v_mfma_f32_16x16x32_bf16 v[40:43], v[168:171], v[204:207], v[40:43]
	v_mfma_f32_16x16x32_bf16 v[28:31], v[160:163], v[212:215], v[28:31]
	v_mfma_f32_16x16x32_bf16 v[24:27], v[168:171], v[212:215], v[24:27]
	v_mfma_f32_16x16x32_bf16 v[12:15], v[160:163], v[220:223], v[12:15]
	v_mfma_f32_16x16x32_bf16 v[8:11], v[168:171], v[220:223], v[8:11]
	v_mfma_f32_16x16x32_bf16 v[52:55], v[172:175], v[192:195], v[52:55]
	v_mfma_f32_16x16x32_bf16 v[48:51], v[184:187], v[192:195], v[48:51]
	v_mfma_f32_16x16x32_bf16 v[36:39], v[172:175], v[200:203], v[36:39]
	v_mfma_f32_16x16x32_bf16 v[32:35], v[184:187], v[200:203], v[32:35]
	v_mfma_f32_16x16x32_bf16 v[20:23], v[172:175], v[208:211], v[20:23]
	v_mfma_f32_16x16x32_bf16 v[16:19], v[184:187], v[208:211], v[16:19]
	v_mfma_f32_16x16x32_bf16 v[4:7], v[172:175], v[216:219], v[4:7]
	v_mfma_f32_16x16x32_bf16 v[0:3], v[184:187], v[216:219], v[0:3]
	v_mfma_f32_16x16x32_bf16 v[52:55], v[180:183], v[196:199], v[52:55]
	v_mfma_f32_16x16x32_bf16 v[48:51], v[188:191], v[196:199], v[48:51]
	v_mfma_f32_16x16x32_bf16 v[36:39], v[180:183], v[204:207], v[36:39]
	v_mfma_f32_16x16x32_bf16 v[32:35], v[188:191], v[204:207], v[32:35]
	v_mfma_f32_16x16x32_bf16 v[20:23], v[180:183], v[212:215], v[20:23]
	v_mfma_f32_16x16x32_bf16 v[16:19], v[188:191], v[212:215], v[16:19]
	v_mfma_f32_16x16x32_bf16 v[4:7], v[180:183], v[220:223], v[4:7]
	v_mfma_f32_16x16x32_bf16 v[0:3], v[188:191], v[220:223], v[0:3]
	s_setprio 0
	s_barrier
	s_add_i32 s78, s78, 2
	s_add_u32 s76, s76, 0x100
	s_addc_u32 s77, s77, 0
	s_cmpk_gt_u32 s78, 0x7d
	s_mov_b64 s[64:65], s[66:67]
	s_cbranch_scc0 .LBB0_810
	s_and_b64 vcc, exec, s[12:13]
	s_cbranch_vccz .LBB0_813
	s_barrier

.LBB0_896:
	ds_read_b128 v[150:153], v160
	ds_read_b128 v[166:169], v160 offset:1024
	ds_read_b128 v[170:173], v160 offset:2048
	ds_read_b128 v[180:183], v160 offset:3072
	ds_read_b128 v[184:187], v161
	ds_read_b128 v[188:191], v161 offset:1024
	ds_read_b128 v[192:195], v161 offset:2048
	ds_read_b128 v[196:199], v161 offset:3072
	s_add_u32 s60, s58, 0x100
	s_addc_u32 s61, s59, 0
	s_cmp_eq_u32 s75, 28
	s_cselect_b32 s65, s1, s61
	s_cselect_b32 s64, s9, s60
	s_cselect_b32 s63, s44, s53
	s_cselect_b32 s62, s45, s49
	v_lshl_add_u64 v[154:155], s[58:59], 0, v[142:143]
	s_add_i32 m0, s21, 0xc000
	ds_read_b128 v[200:203], v162
	ds_read_b128 v[204:207], v162 offset:1024
	ds_read_b128 v[208:211], v162 offset:2048
	ds_read_b128 v[212:215], v162 offset:3072
	ds_read_b128 v[216:219], v162 offset:4096
	ds_read_b128 v[220:223], v162 offset:5120
	ds_read_b128 v[224:227], v162 offset:6144
	ds_read_b128 v[228:231], v162 offset:7168
	global_load_lds_dwordx4 v[154:155], off
	v_lshl_add_u64 v[154:155], s[58:59], 0, v[144:145]
	s_add_i32 m0, s21, 0xe000
	s_nop 0
	global_load_lds_dwordx4 v[154:155], off
	s_waitcnt vmcnt(8)
	s_waitcnt lgkmcnt(0)
	s_barrier
	s_setprio 1
	s_waitcnt lgkmcnt(0)
	v_mfma_f32_16x16x32_bf16 v[124:127], v[150:153], v[200:203], v[124:127]
	v_mfma_f32_16x16x32_bf16 v[120:123], v[170:173], v[200:203], v[120:123]
	v_mfma_f32_16x16x32_bf16 v[108:111], v[150:153], v[208:211], v[108:111]
	v_mfma_f32_16x16x32_bf16 v[104:107], v[170:173], v[208:211], v[104:107]
	v_mfma_f32_16x16x32_bf16 v[92:95], v[150:153], v[216:219], v[92:95]
	v_mfma_f32_16x16x32_bf16 v[88:91], v[170:173], v[216:219], v[88:91]
	v_mfma_f32_16x16x32_bf16 v[76:79], v[150:153], v[224:227], v[76:79]
	v_mfma_f32_16x16x32_bf16 v[72:75], v[170:173], v[224:227], v[72:75]
	v_mfma_f32_16x16x32_bf16 v[124:127], v[166:169], v[204:207], v[124:127]
	v_mfma_f32_16x16x32_bf16 v[120:123], v[180:183], v[204:207], v[120:123]
	v_mfma_f32_16x16x32_bf16 v[108:111], v[166:169], v[212:215], v[108:111]
	v_mfma_f32_16x16x32_bf16 v[104:107], v[180:183], v[212:215], v[104:107]
	v_mfma_f32_16x16x32_bf16 v[92:95], v[166:169], v[220:223], v[92:95]
	v_mfma_f32_16x16x32_bf16 v[88:91], v[180:183], v[220:223], v[88:91]
	v_mfma_f32_16x16x32_bf16 v[76:79], v[166:169], v[228:231], v[76:79]
	v_mfma_f32_16x16x32_bf16 v[72:75], v[180:183], v[228:231], v[72:75]
	v_mfma_f32_16x16x32_bf16 v[116:119], v[184:187], v[200:203], v[116:119]
	v_mfma_f32_16x16x32_bf16 v[112:115], v[192:195], v[200:203], v[112:115]
	v_mfma_f32_16x16x32_bf16 v[100:103], v[184:187], v[208:211], v[100:103]
	v_mfma_f32_16x16x32_bf16 v[96:99], v[192:195], v[208:211], v[96:99]
	v_mfma_f32_16x16x32_bf16 v[84:87], v[184:187], v[216:219], v[84:87]
	v_mfma_f32_16x16x32_bf16 v[80:83], v[192:195], v[216:219], v[80:83]
	v_mfma_f32_16x16x32_bf16 v[68:71], v[184:187], v[224:227], v[68:71]
	v_mfma_f32_16x16x32_bf16 v[64:67], v[192:195], v[224:227], v[64:67]
	v_mfma_f32_16x16x32_bf16 v[116:119], v[188:191], v[204:207], v[116:119]
	v_mfma_f32_16x16x32_bf16 v[112:115], v[196:199], v[204:207], v[112:115]
	v_mfma_f32_16x16x32_bf16 v[100:103], v[188:191], v[212:215], v[100:103]
	v_mfma_f32_16x16x32_bf16 v[96:99], v[196:199], v[212:215], v[96:99]
	v_mfma_f32_16x16x32_bf16 v[84:87], v[188:191], v[220:223], v[84:87]
	v_mfma_f32_16x16x32_bf16 v[80:83], v[196:199], v[220:223], v[80:83]
	v_mfma_f32_16x16x32_bf16 v[68:71], v[188:191], v[228:231], v[68:71]
	v_mfma_f32_16x16x32_bf16 v[64:67], v[196:199], v[228:231], v[64:67]
	s_setprio 0
	s_barrier
	s_add_i32 s58, s72, s88
	v_lshl_add_u64 v[154:155], s[62:63], 0, v[130:131]
	s_mov_b32 m0, s58
	ds_read_b128 v[200:203], v162 offset:16384
	ds_read_b128 v[204:207], v162 offset:17408
	ds_read_b128 v[208:211], v162 offset:18432
	ds_read_b128 v[212:215], v162 offset:19456
	ds_read_b128 v[216:219], v162 offset:20480
	ds_read_b128 v[220:223], v162 offset:21504
	ds_read_b128 v[224:227], v162 offset:22528
	ds_read_b128 v[228:231], v162 offset:23552
	global_load_lds_dwordx4 v[154:155], off
	s_add_i32 m0, s58, 0x2000
	s_add_u32 s58, s62, 0x80000
	v_lshl_add_u64 v[174:175], s[62:63], 0, v[134:135]
	s_addc_u32 s59, s63, 0
	s_add_i32 s76, s73, s88
	global_load_lds_dwordx4 v[174:175], off
	v_lshl_add_u64 v[232:233], s[58:59], 0, v[130:131]
	s_mov_b32 m0, s76
	v_lshl_add_u64 v[234:235], s[64:65], 0, v[132:133]
	global_load_lds_dwordx4 v[232:233], off
	v_lshl_add_u64 v[232:233], s[58:59], 0, v[134:135]
	s_add_i32 m0, s76, 0x2000
	s_nop 0
	global_load_lds_dwordx4 v[232:233], off
	v_lshl_add_u64 v[232:233], s[64:65], 0, v[128:129]
	s_mov_b32 m0, s21
	s_nop 0
	global_load_lds_dwordx4 v[232:233], off
	s_mov_b32 m0, s23
	s_nop 0
	global_load_lds_dwordx4 v[234:235], off
	s_waitcnt vmcnt(8)
	s_waitcnt lgkmcnt(0)
	s_barrier
	s_setprio 1
	s_waitcnt lgkmcnt(0)
	v_mfma_f32_16x16x32_bf16 v[60:63], v[150:153], v[200:203], v[60:63]
	v_mfma_f32_16x16x32_bf16 v[56:59], v[170:173], v[200:203], v[56:59]
	v_mfma_f32_16x16x32_bf16 v[44:47], v[150:153], v[208:211], v[44:47]
	v_mfma_f32_16x16x32_bf16 v[40:43], v[170:173], v[208:211], v[40:43]
	v_mfma_f32_16x16x32_bf16 v[28:31], v[150:153], v[216:219], v[28:31]
	v_mfma_f32_16x16x32_bf16 v[24:27], v[170:173], v[216:219], v[24:27]
	v_mfma_f32_16x16x32_bf16 v[12:15], v[150:153], v[224:227], v[12:15]
	v_mfma_f32_16x16x32_bf16 v[8:11], v[170:173], v[224:227], v[8:11]
	v_mfma_f32_16x16x32_bf16 v[60:63], v[166:169], v[204:207], v[60:63]
	v_mfma_f32_16x16x32_bf16 v[56:59], v[180:183], v[204:207], v[56:59]
	v_mfma_f32_16x16x32_bf16 v[44:47], v[166:169], v[212:215], v[44:47]
	v_mfma_f32_16x16x32_bf16 v[40:43], v[180:183], v[212:215], v[40:43]
	v_mfma_f32_16x16x32_bf16 v[28:31], v[166:169], v[220:223], v[28:31]
	v_mfma_f32_16x16x32_bf16 v[24:27], v[180:183], v[220:223], v[24:27]
	v_mfma_f32_16x16x32_bf16 v[12:15], v[166:169], v[228:231], v[12:15]
	v_mfma_f32_16x16x32_bf16 v[8:11], v[180:183], v[228:231], v[8:11]
	v_mfma_f32_16x16x32_bf16 v[52:55], v[184:187], v[200:203], v[52:55]
	v_mfma_f32_16x16x32_bf16 v[48:51], v[192:195], v[200:203], v[48:51]
	v_mfma_f32_16x16x32_bf16 v[36:39], v[184:187], v[208:211], v[36:39]
	v_mfma_f32_16x16x32_bf16 v[32:35], v[192:195], v[208:211], v[32:35]
	v_mfma_f32_16x16x32_bf16 v[20:23], v[184:187], v[216:219], v[20:23]
	v_mfma_f32_16x16x32_bf16 v[16:19], v[192:195], v[216:219], v[16:19]
	v_mfma_f32_16x16x32_bf16 v[4:7], v[184:187], v[224:227], v[4:7]
	v_mfma_f32_16x16x32_bf16 v[0:3], v[192:195], v[224:227], v[0:3]
	v_mfma_f32_16x16x32_bf16 v[52:55], v[188:191], v[204:207], v[52:55]
	v_mfma_f32_16x16x32_bf16 v[48:51], v[196:199], v[204:207], v[48:51]
	v_mfma_f32_16x16x32_bf16 v[36:39], v[188:191], v[212:215], v[36:39]
	v_mfma_f32_16x16x32_bf16 v[32:35], v[196:199], v[212:215], v[32:35]
	v_mfma_f32_16x16x32_bf16 v[20:23], v[188:191], v[220:223], v[20:23]
	v_mfma_f32_16x16x32_bf16 v[16:19], v[196:199], v[220:223], v[16:19]
	v_mfma_f32_16x16x32_bf16 v[4:7], v[188:191], v[228:231], v[4:7]
	v_mfma_f32_16x16x32_bf16 v[0:3], v[196:199], v[228:231], v[0:3]
	s_setprio 0
	s_barrier
	s_add_i32 s76, 0, 0x18000
	v_add_u32_e32 v136, s76, v139
	s_add_i32 s77, 0, 0x1c000
	ds_read_b128 v[150:153], v136
	ds_read_b128 v[166:169], v136 offset:1024
	ds_read_b128 v[170:173], v136 offset:2048
	ds_read_b128 v[180:183], v136 offset:3072
	v_add_u32_e32 v136, s77, v139
	ds_read_b128 v[184:187], v136
	ds_read_b128 v[188:191], v136 offset:1024
	ds_read_b128 v[192:195], v136 offset:2048
	ds_read_b128 v[196:199], v136 offset:3072
	s_add_u32 s58, s64, 0x80000
	s_addc_u32 s59, s65, 0
	s_mov_b32 m0, s36
	v_lshl_add_u64 v[236:237], s[58:59], 0, v[128:129]
	ds_read_b128 v[200:203], v162 offset:32768
	ds_read_b128 v[204:207], v162 offset:33792
	ds_read_b128 v[208:211], v162 offset:34816
	ds_read_b128 v[212:215], v162 offset:35840
	ds_read_b128 v[216:219], v162 offset:36864
	ds_read_b128 v[220:223], v162 offset:37888
	ds_read_b128 v[224:227], v162 offset:38912
	ds_read_b128 v[228:231], v162 offset:39936
	global_load_lds_dwordx4 v[236:237], off
	v_lshl_add_u64 v[236:237], s[58:59], 0, v[132:133]
	s_mov_b32 m0, s37
	s_nop 0
	global_load_lds_dwordx4 v[236:237], off
	s_waitcnt vmcnt(8)
	s_waitcnt lgkmcnt(0)
	s_barrier
	s_setprio 1
	s_waitcnt lgkmcnt(0)
	v_mfma_f32_16x16x32_bf16 v[124:127], v[150:153], v[200:203], v[124:127]
	v_mfma_f32_16x16x32_bf16 v[120:123], v[170:173], v[200:203], v[120:123]
	v_mfma_f32_16x16x32_bf16 v[108:111], v[150:153], v[208:211], v[108:111]
	v_mfma_f32_16x16x32_bf16 v[104:107], v[170:173], v[208:211], v[104:107]
	v_mfma_f32_16x16x32_bf16 v[92:95], v[150:153], v[216:219], v[92:95]
	v_mfma_f32_16x16x32_bf16 v[88:91], v[170:173], v[216:219], v[88:91]
	v_mfma_f32_16x16x32_bf16 v[76:79], v[150:153], v[224:227], v[76:79]
	v_mfma_f32_16x16x32_bf16 v[72:75], v[170:173], v[224:227], v[72:75]
	v_mfma_f32_16x16x32_bf16 v[124:127], v[166:169], v[204:207], v[124:127]
	v_mfma_f32_16x16x32_bf16 v[120:123], v[180:183], v[204:207], v[120:123]
	v_mfma_f32_16x16x32_bf16 v[108:111], v[166:169], v[212:215], v[108:111]
	v_mfma_f32_16x16x32_bf16 v[104:107], v[180:183], v[212:215], v[104:107]
	v_mfma_f32_16x16x32_bf16 v[92:95], v[166:169], v[220:223], v[92:95]
	v_mfma_f32_16x16x32_bf16 v[88:91], v[180:183], v[220:223], v[88:91]
	v_mfma_f32_16x16x32_bf16 v[76:79], v[166:169], v[228:231], v[76:79]
	v_mfma_f32_16x16x32_bf16 v[72:75], v[180:183], v[228:231], v[72:75]
	v_mfma_f32_16x16x32_bf16 v[116:119], v[184:187], v[200:203], v[116:119]
	v_mfma_f32_16x16x32_bf16 v[112:115], v[192:195], v[200:203], v[112:115]
	v_mfma_f32_16x16x32_bf16 v[100:103], v[184:187], v[208:211], v[100:103]
	v_mfma_f32_16x16x32_bf16 v[96:99], v[192:195], v[208:211], v[96:99]
	v_mfma_f32_16x16x32_bf16 v[84:87], v[184:187], v[216:219], v[84:87]
	v_mfma_f32_16x16x32_bf16 v[80:83], v[192:195], v[216:219], v[80:83]
	v_mfma_f32_16x16x32_bf16 v[68:71], v[184:187], v[224:227], v[68:71]
	v_mfma_f32_16x16x32_bf16 v[64:67], v[192:195], v[224:227], v[64:67]
	v_mfma_f32_16x16x32_bf16 v[116:119], v[188:191], v[204:207], v[116:119]
	v_mfma_f32_16x16x32_bf16 v[112:115], v[196:199], v[204:207], v[112:115]
	v_mfma_f32_16x16x32_bf16 v[100:103], v[188:191], v[212:215], v[100:103]
	v_mfma_f32_16x16x32_bf16 v[96:99], v[196:199], v[212:215], v[96:99]
	v_mfma_f32_16x16x32_bf16 v[84:87], v[188:191], v[220:223], v[84:87]
	v_mfma_f32_16x16x32_bf16 v[80:83], v[196:199], v[220:223], v[80:83]
	v_mfma_f32_16x16x32_bf16 v[68:71], v[188:191], v[228:231], v[68:71]
	v_mfma_f32_16x16x32_bf16 v[64:67], v[196:199], v[228:231], v[64:67]
	s_setprio 0
	s_barrier
	s_add_i32 s58, s76, s88
	v_lshl_add_u64 v[154:155], v[154:155], 0, s[16:17]
	s_mov_b32 m0, s58
	ds_read_b128 v[200:203], v162 offset:49152
	ds_read_b128 v[204:207], v162 offset:50176
	ds_read_b128 v[208:211], v162 offset:51200
	ds_read_b128 v[212:215], v162 offset:52224
	ds_read_b128 v[216:219], v162 offset:53248
	ds_read_b128 v[220:223], v162 offset:54272
	ds_read_b128 v[224:227], v162 offset:55296
	ds_read_b128 v[228:231], v162 offset:56320
	global_load_lds_dwordx4 v[154:155], off
	s_add_i32 m0, s58, 0x2000
	s_add_u32 s58, s62, 0x80080
	v_lshl_add_u64 v[154:155], v[174:175], 0, s[16:17]
	s_addc_u32 s59, s63, 0
	s_add_i32 s62, s77, s88
	global_load_lds_dwordx4 v[154:155], off
	v_lshl_add_u64 v[154:155], s[58:59], 0, v[130:131]
	s_mov_b32 m0, s62
	s_nop 0
	global_load_lds_dwordx4 v[154:155], off
	v_lshl_add_u64 v[154:155], s[58:59], 0, v[134:135]
	s_add_i32 m0, s62, 0x2000
	s_nop 0
	global_load_lds_dwordx4 v[154:155], off
	v_lshl_add_u64 v[154:155], v[232:233], 0, s[16:17]
	s_mov_b32 m0, s67
	s_nop 0
	global_load_lds_dwordx4 v[154:155], off
	v_lshl_add_u64 v[154:155], v[234:235], 0, s[16:17]
	s_mov_b32 m0, s68
	s_nop 0
	global_load_lds_dwordx4 v[154:155], off
	s_waitcnt vmcnt(8)
	s_waitcnt lgkmcnt(0)
	s_barrier
	s_setprio 1
	s_waitcnt lgkmcnt(0)
	v_mfma_f32_16x16x32_bf16 v[60:63], v[150:153], v[200:203], v[60:63]
	v_mfma_f32_16x16x32_bf16 v[56:59], v[170:173], v[200:203], v[56:59]
	v_mfma_f32_16x16x32_bf16 v[44:47], v[150:153], v[208:211], v[44:47]
	v_mfma_f32_16x16x32_bf16 v[40:43], v[170:173], v[208:211], v[40:43]
	v_mfma_f32_16x16x32_bf16 v[28:31], v[150:153], v[216:219], v[28:31]
	v_mfma_f32_16x16x32_bf16 v[24:27], v[170:173], v[216:219], v[24:27]
	v_mfma_f32_16x16x32_bf16 v[12:15], v[150:153], v[224:227], v[12:15]
	v_mfma_f32_16x16x32_bf16 v[8:11], v[170:173], v[224:227], v[8:11]
	v_mfma_f32_16x16x32_bf16 v[60:63], v[166:169], v[204:207], v[60:63]
	v_mfma_f32_16x16x32_bf16 v[56:59], v[180:183], v[204:207], v[56:59]
	v_mfma_f32_16x16x32_bf16 v[44:47], v[166:169], v[212:215], v[44:47]
	v_mfma_f32_16x16x32_bf16 v[40:43], v[180:183], v[212:215], v[40:43]
	v_mfma_f32_16x16x32_bf16 v[28:31], v[166:169], v[220:223], v[28:31]
	v_mfma_f32_16x16x32_bf16 v[24:27], v[180:183], v[220:223], v[24:27]
	v_mfma_f32_16x16x32_bf16 v[12:15], v[166:169], v[228:231], v[12:15]
	v_mfma_f32_16x16x32_bf16 v[8:11], v[180:183], v[228:231], v[8:11]
	v_mfma_f32_16x16x32_bf16 v[52:55], v[184:187], v[200:203], v[52:55]
	v_mfma_f32_16x16x32_bf16 v[48:51], v[192:195], v[200:203], v[48:51]
	v_mfma_f32_16x16x32_bf16 v[36:39], v[184:187], v[208:211], v[36:39]
	v_mfma_f32_16x16x32_bf16 v[32:35], v[192:195], v[208:211], v[32:35]
	v_mfma_f32_16x16x32_bf16 v[20:23], v[184:187], v[216:219], v[20:23]
	v_mfma_f32_16x16x32_bf16 v[16:19], v[192:195], v[216:219], v[16:19]
	v_mfma_f32_16x16x32_bf16 v[4:7], v[184:187], v[224:227], v[4:7]
	v_mfma_f32_16x16x32_bf16 v[0:3], v[192:195], v[224:227], v[0:3]
	v_mfma_f32_16x16x32_bf16 v[52:55], v[188:191], v[204:207], v[52:55]
	v_mfma_f32_16x16x32_bf16 v[48:51], v[196:199], v[204:207], v[48:51]
	v_mfma_f32_16x16x32_bf16 v[36:39], v[188:191], v[212:215], v[36:39]
	v_mfma_f32_16x16x32_bf16 v[32:35], v[196:199], v[212:215], v[32:35]
	v_mfma_f32_16x16x32_bf16 v[20:23], v[188:191], v[220:223], v[20:23]
	v_mfma_f32_16x16x32_bf16 v[16:19], v[196:199], v[220:223], v[16:19]
	v_mfma_f32_16x16x32_bf16 v[4:7], v[188:191], v[228:231], v[4:7]
	v_mfma_f32_16x16x32_bf16 v[0:3], v[196:199], v[228:231], v[0:3]
	s_setprio 0
	s_barrier
	s_add_i32 s75, s75, 2
	s_add_u32 s49, s49, 0x100
	s_addc_u32 s53, s53, 0
	s_cmp_gt_u32 s75, 29
	s_mov_b64 s[58:59], s[60:61]
	s_cbranch_scc0 .LBB0_896
	s_and_b64 vcc, exec, s[10:11]
	s_cbranch_vccz .LBB0_899
	s_barrier

.LBB0_1429:
	ds_read_b128 v[144:147], v153
	ds_read_b128 v[156:159], v153 offset:1024
	ds_read_b128 v[160:163], v153 offset:2048
	ds_read_b128 v[164:167], v153 offset:3072
	ds_read_b128 v[168:171], v154
	ds_read_b128 v[172:175], v154 offset:1024
	ds_read_b128 v[178:181], v154 offset:2048
	ds_read_b128 v[182:185], v154 offset:3072
	s_add_u32 s56, s54, 0x100
	s_addc_u32 s57, s55, 0
	s_cmp_eq_u32 s72, 28
	s_cselect_b32 s61, s45, s57
	s_cselect_b32 s60, s51, s56
	s_cselect_b32 s59, s43, s71
	s_cselect_b32 s58, s69, s70
	v_lshl_add_u64 v[148:149], s[54:55], 0, v[136:137]
	s_add_i32 m0, s21, 0xc000
	ds_read_b128 v[186:189], v155
	ds_read_b128 v[190:193], v155 offset:1024
	ds_read_b128 v[194:197], v155 offset:2048
	ds_read_b128 v[198:201], v155 offset:3072
	ds_read_b128 v[202:205], v155 offset:4096
	ds_read_b128 v[206:209], v155 offset:5120
	ds_read_b128 v[210:213], v155 offset:6144
	ds_read_b128 v[214:217], v155 offset:7168
	global_load_lds_dwordx4 v[148:149], off
	v_lshl_add_u64 v[148:149], s[54:55], 0, v[138:139]
	s_add_i32 m0, s21, 0xe000
	s_nop 0
	global_load_lds_dwordx4 v[148:149], off
	s_waitcnt vmcnt(8)
	s_waitcnt lgkmcnt(0)
	s_barrier
	s_setprio 1
	s_waitcnt lgkmcnt(0)
	v_mfma_f32_16x16x32_bf16 v[124:127], v[144:147], v[186:189], v[124:127]
	v_mfma_f32_16x16x32_bf16 v[120:123], v[160:163], v[186:189], v[120:123]
	v_mfma_f32_16x16x32_bf16 v[108:111], v[144:147], v[194:197], v[108:111]
	v_mfma_f32_16x16x32_bf16 v[104:107], v[160:163], v[194:197], v[104:107]
	v_mfma_f32_16x16x32_bf16 v[92:95], v[144:147], v[202:205], v[92:95]
	v_mfma_f32_16x16x32_bf16 v[88:91], v[160:163], v[202:205], v[88:91]
	v_mfma_f32_16x16x32_bf16 v[76:79], v[144:147], v[210:213], v[76:79]
	v_mfma_f32_16x16x32_bf16 v[72:75], v[160:163], v[210:213], v[72:75]
	v_mfma_f32_16x16x32_bf16 v[124:127], v[156:159], v[190:193], v[124:127]
	v_mfma_f32_16x16x32_bf16 v[120:123], v[164:167], v[190:193], v[120:123]
	v_mfma_f32_16x16x32_bf16 v[108:111], v[156:159], v[198:201], v[108:111]
	v_mfma_f32_16x16x32_bf16 v[104:107], v[164:167], v[198:201], v[104:107]
	v_mfma_f32_16x16x32_bf16 v[92:95], v[156:159], v[206:209], v[92:95]
	v_mfma_f32_16x16x32_bf16 v[88:91], v[164:167], v[206:209], v[88:91]
	v_mfma_f32_16x16x32_bf16 v[76:79], v[156:159], v[214:217], v[76:79]
	v_mfma_f32_16x16x32_bf16 v[72:75], v[164:167], v[214:217], v[72:75]
	v_mfma_f32_16x16x32_bf16 v[116:119], v[168:171], v[186:189], v[116:119]
	v_mfma_f32_16x16x32_bf16 v[112:115], v[178:181], v[186:189], v[112:115]
	v_mfma_f32_16x16x32_bf16 v[100:103], v[168:171], v[194:197], v[100:103]
	v_mfma_f32_16x16x32_bf16 v[96:99], v[178:181], v[194:197], v[96:99]
	v_mfma_f32_16x16x32_bf16 v[84:87], v[168:171], v[202:205], v[84:87]
	v_mfma_f32_16x16x32_bf16 v[80:83], v[178:181], v[202:205], v[80:83]
	v_mfma_f32_16x16x32_bf16 v[68:71], v[168:171], v[210:213], v[68:71]
	v_mfma_f32_16x16x32_bf16 v[64:67], v[178:181], v[210:213], v[64:67]
	v_mfma_f32_16x16x32_bf16 v[116:119], v[172:175], v[190:193], v[116:119]
	v_mfma_f32_16x16x32_bf16 v[112:115], v[182:185], v[190:193], v[112:115]
	v_mfma_f32_16x16x32_bf16 v[100:103], v[172:175], v[198:201], v[100:103]
	v_mfma_f32_16x16x32_bf16 v[96:99], v[182:185], v[198:201], v[96:99]
	v_mfma_f32_16x16x32_bf16 v[84:87], v[172:175], v[206:209], v[84:87]
	v_mfma_f32_16x16x32_bf16 v[80:83], v[182:185], v[206:209], v[80:83]
	v_mfma_f32_16x16x32_bf16 v[68:71], v[172:175], v[214:217], v[68:71]
	v_mfma_f32_16x16x32_bf16 v[64:67], v[182:185], v[214:217], v[64:67]
	s_setprio 0
	s_barrier
	s_add_i32 s54, s67, s88
	v_lshl_add_u64 v[148:149], s[58:59], 0, v[130:131]
	s_mov_b32 m0, s54
	ds_read_b128 v[186:189], v155 offset:16384
	ds_read_b128 v[190:193], v155 offset:17408
	ds_read_b128 v[194:197], v155 offset:18432
	ds_read_b128 v[198:201], v155 offset:19456
	ds_read_b128 v[202:205], v155 offset:20480
	ds_read_b128 v[206:209], v155 offset:21504
	ds_read_b128 v[210:213], v155 offset:22528
	ds_read_b128 v[214:217], v155 offset:23552
	global_load_lds_dwordx4 v[148:149], off
	s_add_i32 m0, s54, 0x2000
	s_add_u32 s54, s58, 0x80000
	v_lshl_add_u64 v[218:219], s[58:59], 0, v[134:135]
	s_addc_u32 s55, s59, 0
	s_add_i32 s73, s68, s88
	global_load_lds_dwordx4 v[218:219], off
	v_lshl_add_u64 v[220:221], s[54:55], 0, v[130:131]
	s_mov_b32 m0, s73
	v_lshl_add_u64 v[222:223], s[60:61], 0, v[132:133]
	global_load_lds_dwordx4 v[220:221], off
	v_lshl_add_u64 v[220:221], s[54:55], 0, v[134:135]
	s_add_i32 m0, s73, 0x2000
	s_nop 0
	global_load_lds_dwordx4 v[220:221], off
	v_lshl_add_u64 v[220:221], s[60:61], 0, v[128:129]
	s_mov_b32 m0, s21
	s_nop 0
	global_load_lds_dwordx4 v[220:221], off
	s_mov_b32 m0, s23
	s_nop 0
	global_load_lds_dwordx4 v[222:223], off
	s_waitcnt vmcnt(8)
	s_waitcnt lgkmcnt(0)
	s_barrier
	s_setprio 1
	s_waitcnt lgkmcnt(0)
	v_mfma_f32_16x16x32_bf16 v[60:63], v[144:147], v[186:189], v[60:63]
	v_mfma_f32_16x16x32_bf16 v[56:59], v[160:163], v[186:189], v[56:59]
	v_mfma_f32_16x16x32_bf16 v[44:47], v[144:147], v[194:197], v[44:47]
	v_mfma_f32_16x16x32_bf16 v[40:43], v[160:163], v[194:197], v[40:43]
	v_mfma_f32_16x16x32_bf16 v[28:31], v[144:147], v[202:205], v[28:31]
	v_mfma_f32_16x16x32_bf16 v[24:27], v[160:163], v[202:205], v[24:27]
	v_mfma_f32_16x16x32_bf16 v[12:15], v[144:147], v[210:213], v[12:15]
	v_mfma_f32_16x16x32_bf16 v[8:11], v[160:163], v[210:213], v[8:11]
	v_mfma_f32_16x16x32_bf16 v[60:63], v[156:159], v[190:193], v[60:63]
	v_mfma_f32_16x16x32_bf16 v[56:59], v[164:167], v[190:193], v[56:59]
	v_mfma_f32_16x16x32_bf16 v[44:47], v[156:159], v[198:201], v[44:47]
	v_mfma_f32_16x16x32_bf16 v[40:43], v[164:167], v[198:201], v[40:43]
	v_mfma_f32_16x16x32_bf16 v[28:31], v[156:159], v[206:209], v[28:31]
	v_mfma_f32_16x16x32_bf16 v[24:27], v[164:167], v[206:209], v[24:27]
	v_mfma_f32_16x16x32_bf16 v[12:15], v[156:159], v[214:217], v[12:15]
	v_mfma_f32_16x16x32_bf16 v[8:11], v[164:167], v[214:217], v[8:11]
	v_mfma_f32_16x16x32_bf16 v[52:55], v[168:171], v[186:189], v[52:55]
	v_mfma_f32_16x16x32_bf16 v[48:51], v[178:181], v[186:189], v[48:51]
	v_mfma_f32_16x16x32_bf16 v[36:39], v[168:171], v[194:197], v[36:39]
	v_mfma_f32_16x16x32_bf16 v[32:35], v[178:181], v[194:197], v[32:35]
	v_mfma_f32_16x16x32_bf16 v[20:23], v[168:171], v[202:205], v[20:23]
	v_mfma_f32_16x16x32_bf16 v[16:19], v[178:181], v[202:205], v[16:19]
	v_mfma_f32_16x16x32_bf16 v[4:7], v[168:171], v[210:213], v[4:7]
	v_mfma_f32_16x16x32_bf16 v[0:3], v[178:181], v[210:213], v[0:3]
	v_mfma_f32_16x16x32_bf16 v[52:55], v[172:175], v[190:193], v[52:55]
	v_mfma_f32_16x16x32_bf16 v[48:51], v[182:185], v[190:193], v[48:51]
	v_mfma_f32_16x16x32_bf16 v[36:39], v[172:175], v[198:201], v[36:39]
	v_mfma_f32_16x16x32_bf16 v[32:35], v[182:185], v[198:201], v[32:35]
	v_mfma_f32_16x16x32_bf16 v[20:23], v[172:175], v[206:209], v[20:23]
	v_mfma_f32_16x16x32_bf16 v[16:19], v[182:185], v[206:209], v[16:19]
	v_mfma_f32_16x16x32_bf16 v[4:7], v[172:175], v[214:217], v[4:7]
	v_mfma_f32_16x16x32_bf16 v[0:3], v[182:185], v[214:217], v[0:3]
	s_setprio 0
	s_barrier
	s_add_i32 s73, 0, 0x18000
	s_add_i32 s74, 0, 0x1c000
	v_add_u32_e32 v164, s73, v150
	v_add_u32_e32 v182, s74, v150
	ds_read_b128 v[144:147], v164
	ds_read_b128 v[156:159], v164 offset:1024
	ds_read_b128 v[160:163], v164 offset:2048
	ds_read_b128 v[164:167], v164 offset:3072
	ds_read_b128 v[168:171], v182
	ds_read_b128 v[172:175], v182 offset:1024
	ds_read_b128 v[178:181], v182 offset:2048
	ds_read_b128 v[182:185], v182 offset:3072
	s_add_u32 s54, s60, 0x80000
	s_addc_u32 s55, s61, 0
	s_mov_b32 m0, s36
	v_lshl_add_u64 v[224:225], s[54:55], 0, v[128:129]
	ds_read_b128 v[186:189], v155 offset:32768
	ds_read_b128 v[190:193], v155 offset:33792
	ds_read_b128 v[194:197], v155 offset:34816
	ds_read_b128 v[198:201], v155 offset:35840
	ds_read_b128 v[202:205], v155 offset:36864
	ds_read_b128 v[206:209], v155 offset:37888
	ds_read_b128 v[210:213], v155 offset:38912
	ds_read_b128 v[214:217], v155 offset:39936
	global_load_lds_dwordx4 v[224:225], off
	v_lshl_add_u64 v[224:225], s[54:55], 0, v[132:133]
	s_mov_b32 m0, s37
	s_nop 0
	global_load_lds_dwordx4 v[224:225], off
	s_waitcnt vmcnt(8)
	s_waitcnt lgkmcnt(0)
	s_barrier
	s_setprio 1
	s_waitcnt lgkmcnt(0)
	v_mfma_f32_16x16x32_bf16 v[124:127], v[144:147], v[186:189], v[124:127]
	v_mfma_f32_16x16x32_bf16 v[120:123], v[160:163], v[186:189], v[120:123]
	v_mfma_f32_16x16x32_bf16 v[108:111], v[144:147], v[194:197], v[108:111]
	v_mfma_f32_16x16x32_bf16 v[104:107], v[160:163], v[194:197], v[104:107]
	v_mfma_f32_16x16x32_bf16 v[92:95], v[144:147], v[202:205], v[92:95]
	v_mfma_f32_16x16x32_bf16 v[88:91], v[160:163], v[202:205], v[88:91]
	v_mfma_f32_16x16x32_bf16 v[76:79], v[144:147], v[210:213], v[76:79]
	v_mfma_f32_16x16x32_bf16 v[72:75], v[160:163], v[210:213], v[72:75]
	v_mfma_f32_16x16x32_bf16 v[124:127], v[156:159], v[190:193], v[124:127]
	v_mfma_f32_16x16x32_bf16 v[120:123], v[164:167], v[190:193], v[120:123]
	v_mfma_f32_16x16x32_bf16 v[108:111], v[156:159], v[198:201], v[108:111]
	v_mfma_f32_16x16x32_bf16 v[104:107], v[164:167], v[198:201], v[104:107]
	v_mfma_f32_16x16x32_bf16 v[92:95], v[156:159], v[206:209], v[92:95]
	v_mfma_f32_16x16x32_bf16 v[88:91], v[164:167], v[206:209], v[88:91]
	v_mfma_f32_16x16x32_bf16 v[76:79], v[156:159], v[214:217], v[76:79]
	v_mfma_f32_16x16x32_bf16 v[72:75], v[164:167], v[214:217], v[72:75]
	v_mfma_f32_16x16x32_bf16 v[116:119], v[168:171], v[186:189], v[116:119]
	v_mfma_f32_16x16x32_bf16 v[112:115], v[178:181], v[186:189], v[112:115]
	v_mfma_f32_16x16x32_bf16 v[100:103], v[168:171], v[194:197], v[100:103]
	v_mfma_f32_16x16x32_bf16 v[96:99], v[178:181], v[194:197], v[96:99]
	v_mfma_f32_16x16x32_bf16 v[84:87], v[168:171], v[202:205], v[84:87]
	v_mfma_f32_16x16x32_bf16 v[80:83], v[178:181], v[202:205], v[80:83]
	v_mfma_f32_16x16x32_bf16 v[68:71], v[168:171], v[210:213], v[68:71]
	v_mfma_f32_16x16x32_bf16 v[64:67], v[178:181], v[210:213], v[64:67]
	v_mfma_f32_16x16x32_bf16 v[116:119], v[172:175], v[190:193], v[116:119]
	v_mfma_f32_16x16x32_bf16 v[112:115], v[182:185], v[190:193], v[112:115]
	v_mfma_f32_16x16x32_bf16 v[100:103], v[172:175], v[198:201], v[100:103]
	v_mfma_f32_16x16x32_bf16 v[96:99], v[182:185], v[198:201], v[96:99]
	v_mfma_f32_16x16x32_bf16 v[84:87], v[172:175], v[206:209], v[84:87]
	v_mfma_f32_16x16x32_bf16 v[80:83], v[182:185], v[206:209], v[80:83]
	v_mfma_f32_16x16x32_bf16 v[68:71], v[172:175], v[214:217], v[68:71]
	v_mfma_f32_16x16x32_bf16 v[64:67], v[182:185], v[214:217], v[64:67]
	s_setprio 0
	s_barrier
	s_add_i32 s54, s73, s88
	v_lshl_add_u64 v[148:149], v[148:149], 0, s[40:41]
	s_mov_b32 m0, s54
	ds_read_b128 v[186:189], v155 offset:49152
	ds_read_b128 v[190:193], v155 offset:50176
	ds_read_b128 v[194:197], v155 offset:51200
	ds_read_b128 v[198:201], v155 offset:52224
	ds_read_b128 v[202:205], v155 offset:53248
	ds_read_b128 v[206:209], v155 offset:54272
	ds_read_b128 v[210:213], v155 offset:55296
	ds_read_b128 v[214:217], v155 offset:56320
	global_load_lds_dwordx4 v[148:149], off
	s_add_i32 m0, s54, 0x2000
	s_add_u32 s54, s58, 0x80080
	v_lshl_add_u64 v[148:149], v[218:219], 0, s[40:41]
	s_addc_u32 s55, s59, 0
	s_add_i32 s58, s74, s88
	global_load_lds_dwordx4 v[148:149], off
	v_lshl_add_u64 v[148:149], s[54:55], 0, v[130:131]
	s_mov_b32 m0, s58
	s_nop 0
	global_load_lds_dwordx4 v[148:149], off
	v_lshl_add_u64 v[148:149], s[54:55], 0, v[134:135]
	s_add_i32 m0, s58, 0x2000
	s_nop 0
	global_load_lds_dwordx4 v[148:149], off
	v_lshl_add_u64 v[148:149], v[220:221], 0, s[40:41]
	s_mov_b32 m0, s62
	s_nop 0
	global_load_lds_dwordx4 v[148:149], off
	v_lshl_add_u64 v[148:149], v[222:223], 0, s[40:41]
	s_mov_b32 m0, s63
	s_nop 0
	global_load_lds_dwordx4 v[148:149], off
	s_waitcnt vmcnt(8)
	s_waitcnt lgkmcnt(0)
	s_barrier
	s_setprio 1
	s_waitcnt lgkmcnt(0)
	v_mfma_f32_16x16x32_bf16 v[60:63], v[144:147], v[186:189], v[60:63]
	v_mfma_f32_16x16x32_bf16 v[56:59], v[160:163], v[186:189], v[56:59]
	v_mfma_f32_16x16x32_bf16 v[44:47], v[144:147], v[194:197], v[44:47]
	v_mfma_f32_16x16x32_bf16 v[40:43], v[160:163], v[194:197], v[40:43]
	v_mfma_f32_16x16x32_bf16 v[28:31], v[144:147], v[202:205], v[28:31]
	v_mfma_f32_16x16x32_bf16 v[24:27], v[160:163], v[202:205], v[24:27]
	v_mfma_f32_16x16x32_bf16 v[12:15], v[144:147], v[210:213], v[12:15]
	v_mfma_f32_16x16x32_bf16 v[8:11], v[160:163], v[210:213], v[8:11]
	v_mfma_f32_16x16x32_bf16 v[60:63], v[156:159], v[190:193], v[60:63]
	v_mfma_f32_16x16x32_bf16 v[56:59], v[164:167], v[190:193], v[56:59]
	v_mfma_f32_16x16x32_bf16 v[44:47], v[156:159], v[198:201], v[44:47]
	v_mfma_f32_16x16x32_bf16 v[40:43], v[164:167], v[198:201], v[40:43]
	v_mfma_f32_16x16x32_bf16 v[28:31], v[156:159], v[206:209], v[28:31]
	v_mfma_f32_16x16x32_bf16 v[24:27], v[164:167], v[206:209], v[24:27]
	v_mfma_f32_16x16x32_bf16 v[12:15], v[156:159], v[214:217], v[12:15]
	v_mfma_f32_16x16x32_bf16 v[8:11], v[164:167], v[214:217], v[8:11]
	v_mfma_f32_16x16x32_bf16 v[52:55], v[168:171], v[186:189], v[52:55]
	v_mfma_f32_16x16x32_bf16 v[48:51], v[178:181], v[186:189], v[48:51]
	v_mfma_f32_16x16x32_bf16 v[36:39], v[168:171], v[194:197], v[36:39]
	v_mfma_f32_16x16x32_bf16 v[32:35], v[178:181], v[194:197], v[32:35]
	v_mfma_f32_16x16x32_bf16 v[20:23], v[168:171], v[202:205], v[20:23]
	v_mfma_f32_16x16x32_bf16 v[16:19], v[178:181], v[202:205], v[16:19]
	v_mfma_f32_16x16x32_bf16 v[4:7], v[168:171], v[210:213], v[4:7]
	v_mfma_f32_16x16x32_bf16 v[0:3], v[178:181], v[210:213], v[0:3]
	v_mfma_f32_16x16x32_bf16 v[52:55], v[172:175], v[190:193], v[52:55]
	v_mfma_f32_16x16x32_bf16 v[48:51], v[182:185], v[190:193], v[48:51]
	v_mfma_f32_16x16x32_bf16 v[36:39], v[172:175], v[198:201], v[36:39]
	v_mfma_f32_16x16x32_bf16 v[32:35], v[182:185], v[198:201], v[32:35]
	v_mfma_f32_16x16x32_bf16 v[20:23], v[172:175], v[206:209], v[20:23]
	v_mfma_f32_16x16x32_bf16 v[16:19], v[182:185], v[206:209], v[16:19]
	v_mfma_f32_16x16x32_bf16 v[4:7], v[172:175], v[214:217], v[4:7]
	v_mfma_f32_16x16x32_bf16 v[0:3], v[182:185], v[214:217], v[0:3]
	s_setprio 0
	s_barrier
	s_add_i32 s72, s72, 2
	s_add_u32 s70, s70, 0x100
	s_addc_u32 s71, s71, 0
	s_cmp_gt_u32 s72, 29
	s_mov_b64 s[54:55], s[56:57]
	s_cbranch_scc0 .LBB0_1429
	s_and_b64 vcc, exec, s[12:13]
	s_cbranch_vccz .LBB0_1432
	s_barrier

.LBB0_1521:
	ds_read_b128 v[144:147], v151
	ds_read_b128 v[156:159], v151 offset:1024
	ds_read_b128 v[160:163], v151 offset:2048
	ds_read_b128 v[164:167], v151 offset:3072
	ds_read_b128 v[168:171], v152
	ds_read_b128 v[172:175], v152 offset:1024
	ds_read_b128 v[178:181], v152 offset:2048
	ds_read_b128 v[182:185], v152 offset:3072
	s_add_u32 s46, s44, 0x100
	s_addc_u32 s47, s45, 0
	s_cmp_eq_u32 s67, 28
	s_cselect_b32 s51, s39, s47
	s_cselect_b32 s50, s63, s46
	s_cselect_b32 s49, s37, s66
	s_cselect_b32 s48, s64, s65
	v_lshl_add_u64 v[218:219], s[44:45], 0, v[136:137]
	s_add_i32 m0, s23, 0xc000
	ds_read_b128 v[186:189], v153
	ds_read_b128 v[190:193], v153 offset:1024
	ds_read_b128 v[194:197], v153 offset:2048
	ds_read_b128 v[198:201], v153 offset:3072
	ds_read_b128 v[202:205], v153 offset:4096
	ds_read_b128 v[206:209], v153 offset:5120
	ds_read_b128 v[210:213], v153 offset:6144
	ds_read_b128 v[214:217], v153 offset:7168
	global_load_lds_dwordx4 v[218:219], off
	v_lshl_add_u64 v[218:219], s[44:45], 0, v[138:139]
	s_add_i32 m0, s23, 0xe000
	s_nop 0
	global_load_lds_dwordx4 v[218:219], off
	s_waitcnt vmcnt(8)
	s_waitcnt lgkmcnt(0)
	s_barrier
	s_setprio 1
	s_waitcnt lgkmcnt(0)
	v_mfma_f32_16x16x32_bf16 v[124:127], v[144:147], v[186:189], v[124:127]
	v_mfma_f32_16x16x32_bf16 v[120:123], v[160:163], v[186:189], v[120:123]
	v_mfma_f32_16x16x32_bf16 v[108:111], v[144:147], v[194:197], v[108:111]
	v_mfma_f32_16x16x32_bf16 v[104:107], v[160:163], v[194:197], v[104:107]
	v_mfma_f32_16x16x32_bf16 v[92:95], v[144:147], v[202:205], v[92:95]
	v_mfma_f32_16x16x32_bf16 v[88:91], v[160:163], v[202:205], v[88:91]
	v_mfma_f32_16x16x32_bf16 v[76:79], v[144:147], v[210:213], v[76:79]
	v_mfma_f32_16x16x32_bf16 v[72:75], v[160:163], v[210:213], v[72:75]
	v_mfma_f32_16x16x32_bf16 v[124:127], v[156:159], v[190:193], v[124:127]
	v_mfma_f32_16x16x32_bf16 v[120:123], v[164:167], v[190:193], v[120:123]
	v_mfma_f32_16x16x32_bf16 v[108:111], v[156:159], v[198:201], v[108:111]
	v_mfma_f32_16x16x32_bf16 v[104:107], v[164:167], v[198:201], v[104:107]
	v_mfma_f32_16x16x32_bf16 v[92:95], v[156:159], v[206:209], v[92:95]
	v_mfma_f32_16x16x32_bf16 v[88:91], v[164:167], v[206:209], v[88:91]
	v_mfma_f32_16x16x32_bf16 v[76:79], v[156:159], v[214:217], v[76:79]
	v_mfma_f32_16x16x32_bf16 v[72:75], v[164:167], v[214:217], v[72:75]
	v_mfma_f32_16x16x32_bf16 v[116:119], v[168:171], v[186:189], v[116:119]
	v_mfma_f32_16x16x32_bf16 v[112:115], v[178:181], v[186:189], v[112:115]
	v_mfma_f32_16x16x32_bf16 v[100:103], v[168:171], v[194:197], v[100:103]
	v_mfma_f32_16x16x32_bf16 v[96:99], v[178:181], v[194:197], v[96:99]
	v_mfma_f32_16x16x32_bf16 v[84:87], v[168:171], v[202:205], v[84:87]
	v_mfma_f32_16x16x32_bf16 v[80:83], v[178:181], v[202:205], v[80:83]
	v_mfma_f32_16x16x32_bf16 v[68:71], v[168:171], v[210:213], v[68:71]
	v_mfma_f32_16x16x32_bf16 v[64:67], v[178:181], v[210:213], v[64:67]
	v_mfma_f32_16x16x32_bf16 v[116:119], v[172:175], v[190:193], v[116:119]
	v_mfma_f32_16x16x32_bf16 v[112:115], v[182:185], v[190:193], v[112:115]
	v_mfma_f32_16x16x32_bf16 v[100:103], v[172:175], v[198:201], v[100:103]
	v_mfma_f32_16x16x32_bf16 v[96:99], v[182:185], v[198:201], v[96:99]
	v_mfma_f32_16x16x32_bf16 v[84:87], v[172:175], v[206:209], v[84:87]
	v_mfma_f32_16x16x32_bf16 v[80:83], v[182:185], v[206:209], v[80:83]
	v_mfma_f32_16x16x32_bf16 v[68:71], v[172:175], v[214:217], v[68:71]
	v_mfma_f32_16x16x32_bf16 v[64:67], v[182:185], v[214:217], v[64:67]
	s_setprio 0
	s_barrier
	s_add_i32 s44, s60, s88
	v_lshl_add_u64 v[218:219], s[48:49], 0, v[130:131]
	s_mov_b32 m0, s44
	ds_read_b128 v[186:189], v153 offset:16384
	ds_read_b128 v[190:193], v153 offset:17408
	ds_read_b128 v[194:197], v153 offset:18432
	ds_read_b128 v[198:201], v153 offset:19456
	ds_read_b128 v[202:205], v153 offset:20480
	ds_read_b128 v[206:209], v153 offset:21504
	ds_read_b128 v[210:213], v153 offset:22528
	ds_read_b128 v[214:217], v153 offset:23552
	global_load_lds_dwordx4 v[218:219], off
	s_add_i32 m0, s44, 0x2000
	s_add_u32 s44, s48, 0x80000
	v_lshl_add_u64 v[220:221], s[48:49], 0, v[134:135]
	s_addc_u32 s45, s49, 0
	s_add_i32 s68, s61, s88
	global_load_lds_dwordx4 v[220:221], off
	v_lshl_add_u64 v[222:223], s[44:45], 0, v[130:131]
	s_mov_b32 m0, s68
	v_lshl_add_u64 v[224:225], s[50:51], 0, v[132:133]
	global_load_lds_dwordx4 v[222:223], off
	v_lshl_add_u64 v[222:223], s[44:45], 0, v[134:135]
	s_add_i32 m0, s68, 0x2000
	s_nop 0
	global_load_lds_dwordx4 v[222:223], off
	v_lshl_add_u64 v[222:223], s[50:51], 0, v[128:129]
	s_mov_b32 m0, s23
	s_nop 0
	global_load_lds_dwordx4 v[222:223], off
	s_mov_b32 m0, s52
	s_nop 0
	global_load_lds_dwordx4 v[224:225], off
	s_waitcnt vmcnt(8)
	s_waitcnt lgkmcnt(0)
	s_barrier
	s_setprio 1
	s_waitcnt lgkmcnt(0)
	v_mfma_f32_16x16x32_bf16 v[60:63], v[144:147], v[186:189], v[60:63]
	v_mfma_f32_16x16x32_bf16 v[56:59], v[160:163], v[186:189], v[56:59]
	v_mfma_f32_16x16x32_bf16 v[44:47], v[144:147], v[194:197], v[44:47]
	v_mfma_f32_16x16x32_bf16 v[40:43], v[160:163], v[194:197], v[40:43]
	v_mfma_f32_16x16x32_bf16 v[28:31], v[144:147], v[202:205], v[28:31]
	v_mfma_f32_16x16x32_bf16 v[24:27], v[160:163], v[202:205], v[24:27]
	v_mfma_f32_16x16x32_bf16 v[12:15], v[144:147], v[210:213], v[12:15]
	v_mfma_f32_16x16x32_bf16 v[8:11], v[160:163], v[210:213], v[8:11]
	v_mfma_f32_16x16x32_bf16 v[60:63], v[156:159], v[190:193], v[60:63]
	v_mfma_f32_16x16x32_bf16 v[56:59], v[164:167], v[190:193], v[56:59]
	v_mfma_f32_16x16x32_bf16 v[44:47], v[156:159], v[198:201], v[44:47]
	v_mfma_f32_16x16x32_bf16 v[40:43], v[164:167], v[198:201], v[40:43]
	v_mfma_f32_16x16x32_bf16 v[28:31], v[156:159], v[206:209], v[28:31]
	v_mfma_f32_16x16x32_bf16 v[24:27], v[164:167], v[206:209], v[24:27]
	v_mfma_f32_16x16x32_bf16 v[12:15], v[156:159], v[214:217], v[12:15]
	v_mfma_f32_16x16x32_bf16 v[8:11], v[164:167], v[214:217], v[8:11]
	v_mfma_f32_16x16x32_bf16 v[52:55], v[168:171], v[186:189], v[52:55]
	v_mfma_f32_16x16x32_bf16 v[48:51], v[178:181], v[186:189], v[48:51]
	v_mfma_f32_16x16x32_bf16 v[36:39], v[168:171], v[194:197], v[36:39]
	v_mfma_f32_16x16x32_bf16 v[32:35], v[178:181], v[194:197], v[32:35]
	v_mfma_f32_16x16x32_bf16 v[20:23], v[168:171], v[202:205], v[20:23]
	v_mfma_f32_16x16x32_bf16 v[16:19], v[178:181], v[202:205], v[16:19]
	v_mfma_f32_16x16x32_bf16 v[4:7], v[168:171], v[210:213], v[4:7]
	v_mfma_f32_16x16x32_bf16 v[0:3], v[178:181], v[210:213], v[0:3]
	v_mfma_f32_16x16x32_bf16 v[52:55], v[172:175], v[190:193], v[52:55]
	v_mfma_f32_16x16x32_bf16 v[48:51], v[182:185], v[190:193], v[48:51]
	v_mfma_f32_16x16x32_bf16 v[36:39], v[172:175], v[198:201], v[36:39]
	v_mfma_f32_16x16x32_bf16 v[32:35], v[182:185], v[198:201], v[32:35]
	v_mfma_f32_16x16x32_bf16 v[20:23], v[172:175], v[206:209], v[20:23]
	v_mfma_f32_16x16x32_bf16 v[16:19], v[182:185], v[206:209], v[16:19]
	v_mfma_f32_16x16x32_bf16 v[4:7], v[172:175], v[214:217], v[4:7]
	v_mfma_f32_16x16x32_bf16 v[0:3], v[182:185], v[214:217], v[0:3]
	s_setprio 0
	s_barrier
	s_add_i32 s68, 0, 0x18000
	s_add_i32 s69, 0, 0x1c000
	v_add_u32_e32 v164, s68, v148
	v_add_u32_e32 v182, s69, v148
	ds_read_b128 v[144:147], v164
	ds_read_b128 v[156:159], v164 offset:1024
	ds_read_b128 v[160:163], v164 offset:2048
	ds_read_b128 v[164:167], v164 offset:3072
	ds_read_b128 v[168:171], v182
	ds_read_b128 v[172:175], v182 offset:1024
	ds_read_b128 v[178:181], v182 offset:2048
	ds_read_b128 v[182:185], v182 offset:3072
	s_add_u32 s44, s50, 0x80000
	s_addc_u32 s45, s51, 0
	s_mov_b32 m0, s53
	v_lshl_add_u64 v[226:227], s[44:45], 0, v[128:129]
	ds_read_b128 v[186:189], v153 offset:32768
	ds_read_b128 v[190:193], v153 offset:33792
	ds_read_b128 v[194:197], v153 offset:34816
	ds_read_b128 v[198:201], v153 offset:35840
	ds_read_b128 v[202:205], v153 offset:36864
	ds_read_b128 v[206:209], v153 offset:37888
	ds_read_b128 v[210:213], v153 offset:38912
	ds_read_b128 v[214:217], v153 offset:39936
	global_load_lds_dwordx4 v[226:227], off
	v_lshl_add_u64 v[226:227], s[44:45], 0, v[132:133]
	s_mov_b32 m0, s54
	s_nop 0
	global_load_lds_dwordx4 v[226:227], off
	s_waitcnt vmcnt(8)
	s_waitcnt lgkmcnt(0)
	s_barrier
	s_setprio 1
	s_waitcnt lgkmcnt(0)
	v_mfma_f32_16x16x32_bf16 v[124:127], v[144:147], v[186:189], v[124:127]
	v_mfma_f32_16x16x32_bf16 v[120:123], v[160:163], v[186:189], v[120:123]
	v_mfma_f32_16x16x32_bf16 v[108:111], v[144:147], v[194:197], v[108:111]
	v_mfma_f32_16x16x32_bf16 v[104:107], v[160:163], v[194:197], v[104:107]
	v_mfma_f32_16x16x32_bf16 v[92:95], v[144:147], v[202:205], v[92:95]
	v_mfma_f32_16x16x32_bf16 v[88:91], v[160:163], v[202:205], v[88:91]
	v_mfma_f32_16x16x32_bf16 v[76:79], v[144:147], v[210:213], v[76:79]
	v_mfma_f32_16x16x32_bf16 v[72:75], v[160:163], v[210:213], v[72:75]
	v_mfma_f32_16x16x32_bf16 v[124:127], v[156:159], v[190:193], v[124:127]
	v_mfma_f32_16x16x32_bf16 v[120:123], v[164:167], v[190:193], v[120:123]
	v_mfma_f32_16x16x32_bf16 v[108:111], v[156:159], v[198:201], v[108:111]
	v_mfma_f32_16x16x32_bf16 v[104:107], v[164:167], v[198:201], v[104:107]
	v_mfma_f32_16x16x32_bf16 v[92:95], v[156:159], v[206:209], v[92:95]
	v_mfma_f32_16x16x32_bf16 v[88:91], v[164:167], v[206:209], v[88:91]
	v_mfma_f32_16x16x32_bf16 v[76:79], v[156:159], v[214:217], v[76:79]
	v_mfma_f32_16x16x32_bf16 v[72:75], v[164:167], v[214:217], v[72:75]
	v_mfma_f32_16x16x32_bf16 v[116:119], v[168:171], v[186:189], v[116:119]
	v_mfma_f32_16x16x32_bf16 v[112:115], v[178:181], v[186:189], v[112:115]
	v_mfma_f32_16x16x32_bf16 v[100:103], v[168:171], v[194:197], v[100:103]
	v_mfma_f32_16x16x32_bf16 v[96:99], v[178:181], v[194:197], v[96:99]
	v_mfma_f32_16x16x32_bf16 v[84:87], v[168:171], v[202:205], v[84:87]
	v_mfma_f32_16x16x32_bf16 v[80:83], v[178:181], v[202:205], v[80:83]
	v_mfma_f32_16x16x32_bf16 v[68:71], v[168:171], v[210:213], v[68:71]
	v_mfma_f32_16x16x32_bf16 v[64:67], v[178:181], v[210:213], v[64:67]
	v_mfma_f32_16x16x32_bf16 v[116:119], v[172:175], v[190:193], v[116:119]
	v_mfma_f32_16x16x32_bf16 v[112:115], v[182:185], v[190:193], v[112:115]
	v_mfma_f32_16x16x32_bf16 v[100:103], v[172:175], v[198:201], v[100:103]
	v_mfma_f32_16x16x32_bf16 v[96:99], v[182:185], v[198:201], v[96:99]
	v_mfma_f32_16x16x32_bf16 v[84:87], v[172:175], v[206:209], v[84:87]
	v_mfma_f32_16x16x32_bf16 v[80:83], v[182:185], v[206:209], v[80:83]
	v_mfma_f32_16x16x32_bf16 v[68:71], v[172:175], v[214:217], v[68:71]
	v_mfma_f32_16x16x32_bf16 v[64:67], v[182:185], v[214:217], v[64:67]
	s_setprio 0
	s_barrier
	s_add_i32 s44, s68, s88
	v_lshl_add_u64 v[218:219], v[218:219], 0, s[16:17]
	s_mov_b32 m0, s44
	ds_read_b128 v[186:189], v153 offset:49152
	ds_read_b128 v[190:193], v153 offset:50176
	ds_read_b128 v[194:197], v153 offset:51200
	ds_read_b128 v[198:201], v153 offset:52224
	ds_read_b128 v[202:205], v153 offset:53248
	ds_read_b128 v[206:209], v153 offset:54272
	ds_read_b128 v[210:213], v153 offset:55296
	ds_read_b128 v[214:217], v153 offset:56320
	global_load_lds_dwordx4 v[218:219], off
	s_add_i32 m0, s44, 0x2000
	s_add_u32 s44, s48, 0x80080
	v_lshl_add_u64 v[218:219], v[220:221], 0, s[16:17]
	s_addc_u32 s45, s49, 0
	s_add_i32 s48, s69, s88
	global_load_lds_dwordx4 v[218:219], off
	v_lshl_add_u64 v[218:219], s[44:45], 0, v[130:131]
	s_mov_b32 m0, s48
	s_nop 0
	global_load_lds_dwordx4 v[218:219], off
	v_lshl_add_u64 v[218:219], s[44:45], 0, v[134:135]
	s_add_i32 m0, s48, 0x2000
	s_nop 0
	global_load_lds_dwordx4 v[218:219], off
	v_lshl_add_u64 v[218:219], v[222:223], 0, s[16:17]
	s_mov_b32 m0, s56
	s_nop 0
	global_load_lds_dwordx4 v[218:219], off
	v_lshl_add_u64 v[218:219], v[224:225], 0, s[16:17]
	s_mov_b32 m0, s57
	s_nop 0
	global_load_lds_dwordx4 v[218:219], off
	s_waitcnt vmcnt(8)
	s_waitcnt lgkmcnt(0)
	s_barrier
	s_setprio 1
	s_waitcnt lgkmcnt(0)
	v_mfma_f32_16x16x32_bf16 v[60:63], v[144:147], v[186:189], v[60:63]
	v_mfma_f32_16x16x32_bf16 v[56:59], v[160:163], v[186:189], v[56:59]
	v_mfma_f32_16x16x32_bf16 v[44:47], v[144:147], v[194:197], v[44:47]
	v_mfma_f32_16x16x32_bf16 v[40:43], v[160:163], v[194:197], v[40:43]
	v_mfma_f32_16x16x32_bf16 v[28:31], v[144:147], v[202:205], v[28:31]
	v_mfma_f32_16x16x32_bf16 v[24:27], v[160:163], v[202:205], v[24:27]
	v_mfma_f32_16x16x32_bf16 v[12:15], v[144:147], v[210:213], v[12:15]
	v_mfma_f32_16x16x32_bf16 v[8:11], v[160:163], v[210:213], v[8:11]
	v_mfma_f32_16x16x32_bf16 v[60:63], v[156:159], v[190:193], v[60:63]
	v_mfma_f32_16x16x32_bf16 v[56:59], v[164:167], v[190:193], v[56:59]
	v_mfma_f32_16x16x32_bf16 v[44:47], v[156:159], v[198:201], v[44:47]
	v_mfma_f32_16x16x32_bf16 v[40:43], v[164:167], v[198:201], v[40:43]
	v_mfma_f32_16x16x32_bf16 v[28:31], v[156:159], v[206:209], v[28:31]
	v_mfma_f32_16x16x32_bf16 v[24:27], v[164:167], v[206:209], v[24:27]
	v_mfma_f32_16x16x32_bf16 v[12:15], v[156:159], v[214:217], v[12:15]
	v_mfma_f32_16x16x32_bf16 v[8:11], v[164:167], v[214:217], v[8:11]
	v_mfma_f32_16x16x32_bf16 v[52:55], v[168:171], v[186:189], v[52:55]
	v_mfma_f32_16x16x32_bf16 v[48:51], v[178:181], v[186:189], v[48:51]
	v_mfma_f32_16x16x32_bf16 v[36:39], v[168:171], v[194:197], v[36:39]
	v_mfma_f32_16x16x32_bf16 v[32:35], v[178:181], v[194:197], v[32:35]
	v_mfma_f32_16x16x32_bf16 v[20:23], v[168:171], v[202:205], v[20:23]
	v_mfma_f32_16x16x32_bf16 v[16:19], v[178:181], v[202:205], v[16:19]
	v_mfma_f32_16x16x32_bf16 v[4:7], v[168:171], v[210:213], v[4:7]
	v_mfma_f32_16x16x32_bf16 v[0:3], v[178:181], v[210:213], v[0:3]
	v_mfma_f32_16x16x32_bf16 v[52:55], v[172:175], v[190:193], v[52:55]
	v_mfma_f32_16x16x32_bf16 v[48:51], v[182:185], v[190:193], v[48:51]
	v_mfma_f32_16x16x32_bf16 v[36:39], v[172:175], v[198:201], v[36:39]
	v_mfma_f32_16x16x32_bf16 v[32:35], v[182:185], v[198:201], v[32:35]
	v_mfma_f32_16x16x32_bf16 v[20:23], v[172:175], v[206:209], v[20:23]
	v_mfma_f32_16x16x32_bf16 v[16:19], v[182:185], v[206:209], v[16:19]
	v_mfma_f32_16x16x32_bf16 v[4:7], v[172:175], v[214:217], v[4:7]
	v_mfma_f32_16x16x32_bf16 v[0:3], v[182:185], v[214:217], v[0:3]
	s_setprio 0
	s_barrier
	s_add_i32 s67, s67, 2
	s_add_u32 s65, s65, 0x100
	s_addc_u32 s66, s66, 0
	s_cmp_gt_u32 s67, 29
	s_mov_b64 s[44:45], s[46:47]
	s_cbranch_scc0 .LBB0_1521
	s_and_b64 vcc, exec, s[8:9]
	s_cbranch_vccz .LBB0_1524
	s_barrier

.LBB0_1599:
	ds_read_b128 v[144:147], v151
	ds_read_b128 v[154:157], v151 offset:1024
	ds_read_b128 v[158:161], v151 offset:2048
	ds_read_b128 v[162:165], v151 offset:3072
	ds_read_b128 v[166:169], v152
	ds_read_b128 v[170:173], v152 offset:1024
	ds_read_b128 v[178:181], v152 offset:2048
	ds_read_b128 v[182:185], v152 offset:3072
	s_add_u32 s50, s48, 0x100
	s_addc_u32 s51, s49, 0
	s_cmpk_eq_i32 s68, 0x7c
	s_cselect_b32 s55, s39, s51
	s_cselect_b32 s54, s45, s50
	s_cselect_b32 s53, s37, s67
	s_cselect_b32 s52, s65, s66
	v_lshl_add_u64 v[174:175], s[48:49], 0, v[136:137]
	s_add_i32 m0, s21, 0xc000
	ds_read_b128 v[186:189], v153
	ds_read_b128 v[190:193], v153 offset:1024
	ds_read_b128 v[194:197], v153 offset:2048
	ds_read_b128 v[198:201], v153 offset:3072
	ds_read_b128 v[202:205], v153 offset:4096
	ds_read_b128 v[206:209], v153 offset:5120
	ds_read_b128 v[210:213], v153 offset:6144
	ds_read_b128 v[214:217], v153 offset:7168
	global_load_lds_dwordx4 v[174:175], off
	v_lshl_add_u64 v[174:175], s[48:49], 0, v[138:139]
	s_add_i32 m0, s21, 0xe000
	s_nop 0
	global_load_lds_dwordx4 v[174:175], off
	s_waitcnt vmcnt(8)
	s_waitcnt lgkmcnt(0)
	s_barrier
	s_setprio 1
	s_waitcnt lgkmcnt(0)
	v_mfma_f32_16x16x32_bf16 v[124:127], v[144:147], v[186:189], v[124:127]
	v_mfma_f32_16x16x32_bf16 v[120:123], v[158:161], v[186:189], v[120:123]
	v_mfma_f32_16x16x32_bf16 v[108:111], v[144:147], v[194:197], v[108:111]
	v_mfma_f32_16x16x32_bf16 v[104:107], v[158:161], v[194:197], v[104:107]
	v_mfma_f32_16x16x32_bf16 v[92:95], v[144:147], v[202:205], v[92:95]
	v_mfma_f32_16x16x32_bf16 v[88:91], v[158:161], v[202:205], v[88:91]
	v_mfma_f32_16x16x32_bf16 v[76:79], v[144:147], v[210:213], v[76:79]
	v_mfma_f32_16x16x32_bf16 v[72:75], v[158:161], v[210:213], v[72:75]
	v_mfma_f32_16x16x32_bf16 v[124:127], v[154:157], v[190:193], v[124:127]
	v_mfma_f32_16x16x32_bf16 v[120:123], v[162:165], v[190:193], v[120:123]
	v_mfma_f32_16x16x32_bf16 v[108:111], v[154:157], v[198:201], v[108:111]
	v_mfma_f32_16x16x32_bf16 v[104:107], v[162:165], v[198:201], v[104:107]
	v_mfma_f32_16x16x32_bf16 v[92:95], v[154:157], v[206:209], v[92:95]
	v_mfma_f32_16x16x32_bf16 v[88:91], v[162:165], v[206:209], v[88:91]
	v_mfma_f32_16x16x32_bf16 v[76:79], v[154:157], v[214:217], v[76:79]
	v_mfma_f32_16x16x32_bf16 v[72:75], v[162:165], v[214:217], v[72:75]
	v_mfma_f32_16x16x32_bf16 v[116:119], v[166:169], v[186:189], v[116:119]
	v_mfma_f32_16x16x32_bf16 v[112:115], v[178:181], v[186:189], v[112:115]
	v_mfma_f32_16x16x32_bf16 v[100:103], v[166:169], v[194:197], v[100:103]
	v_mfma_f32_16x16x32_bf16 v[96:99], v[178:181], v[194:197], v[96:99]
	v_mfma_f32_16x16x32_bf16 v[84:87], v[166:169], v[202:205], v[84:87]
	v_mfma_f32_16x16x32_bf16 v[80:83], v[178:181], v[202:205], v[80:83]
	v_mfma_f32_16x16x32_bf16 v[68:71], v[166:169], v[210:213], v[68:71]
	v_mfma_f32_16x16x32_bf16 v[64:67], v[178:181], v[210:213], v[64:67]
	v_mfma_f32_16x16x32_bf16 v[116:119], v[170:173], v[190:193], v[116:119]
	v_mfma_f32_16x16x32_bf16 v[112:115], v[182:185], v[190:193], v[112:115]
	v_mfma_f32_16x16x32_bf16 v[100:103], v[170:173], v[198:201], v[100:103]
	v_mfma_f32_16x16x32_bf16 v[96:99], v[182:185], v[198:201], v[96:99]
	v_mfma_f32_16x16x32_bf16 v[84:87], v[170:173], v[206:209], v[84:87]
	v_mfma_f32_16x16x32_bf16 v[80:83], v[182:185], v[206:209], v[80:83]
	v_mfma_f32_16x16x32_bf16 v[68:71], v[170:173], v[214:217], v[68:71]
	v_mfma_f32_16x16x32_bf16 v[64:67], v[182:185], v[214:217], v[64:67]
	s_setprio 0
	s_barrier
	s_add_i32 s48, s63, s88
	v_lshl_add_u64 v[174:175], s[52:53], 0, v[130:131]
	s_mov_b32 m0, s48
	ds_read_b128 v[186:189], v153 offset:16384
	ds_read_b128 v[190:193], v153 offset:17408
	ds_read_b128 v[194:197], v153 offset:18432
	ds_read_b128 v[198:201], v153 offset:19456
	ds_read_b128 v[202:205], v153 offset:20480
	ds_read_b128 v[206:209], v153 offset:21504
	ds_read_b128 v[210:213], v153 offset:22528
	ds_read_b128 v[214:217], v153 offset:23552
	global_load_lds_dwordx4 v[174:175], off
	s_add_i32 m0, s48, 0x2000
	s_add_u32 s48, s52, 0x200000
	v_lshl_add_u64 v[218:219], s[52:53], 0, v[134:135]
	s_addc_u32 s49, s53, 0
	s_add_i32 s69, s64, s88
	global_load_lds_dwordx4 v[218:219], off
	v_lshl_add_u64 v[220:221], s[48:49], 0, v[130:131]
	s_mov_b32 m0, s69
	v_lshl_add_u64 v[222:223], s[54:55], 0, v[132:133]
	global_load_lds_dwordx4 v[220:221], off
	v_lshl_add_u64 v[220:221], s[48:49], 0, v[134:135]
	s_add_i32 m0, s69, 0x2000
	s_nop 0
	global_load_lds_dwordx4 v[220:221], off
	v_lshl_add_u64 v[220:221], s[54:55], 0, v[128:129]
	s_mov_b32 m0, s21
	s_nop 0
	global_load_lds_dwordx4 v[220:221], off
	s_mov_b32 m0, s23
	s_nop 0
	global_load_lds_dwordx4 v[222:223], off
	s_waitcnt vmcnt(8)
	s_waitcnt lgkmcnt(0)
	s_barrier
	s_setprio 1
	s_waitcnt lgkmcnt(0)
	v_mfma_f32_16x16x32_bf16 v[60:63], v[144:147], v[186:189], v[60:63]
	v_mfma_f32_16x16x32_bf16 v[56:59], v[158:161], v[186:189], v[56:59]
	v_mfma_f32_16x16x32_bf16 v[44:47], v[144:147], v[194:197], v[44:47]
	v_mfma_f32_16x16x32_bf16 v[40:43], v[158:161], v[194:197], v[40:43]
	v_mfma_f32_16x16x32_bf16 v[28:31], v[144:147], v[202:205], v[28:31]
	v_mfma_f32_16x16x32_bf16 v[24:27], v[158:161], v[202:205], v[24:27]
	v_mfma_f32_16x16x32_bf16 v[12:15], v[144:147], v[210:213], v[12:15]
	v_mfma_f32_16x16x32_bf16 v[8:11], v[158:161], v[210:213], v[8:11]
	v_mfma_f32_16x16x32_bf16 v[60:63], v[154:157], v[190:193], v[60:63]
	v_mfma_f32_16x16x32_bf16 v[56:59], v[162:165], v[190:193], v[56:59]
	v_mfma_f32_16x16x32_bf16 v[44:47], v[154:157], v[198:201], v[44:47]
	v_mfma_f32_16x16x32_bf16 v[40:43], v[162:165], v[198:201], v[40:43]
	v_mfma_f32_16x16x32_bf16 v[28:31], v[154:157], v[206:209], v[28:31]
	v_mfma_f32_16x16x32_bf16 v[24:27], v[162:165], v[206:209], v[24:27]
	v_mfma_f32_16x16x32_bf16 v[12:15], v[154:157], v[214:217], v[12:15]
	v_mfma_f32_16x16x32_bf16 v[8:11], v[162:165], v[214:217], v[8:11]
	v_mfma_f32_16x16x32_bf16 v[52:55], v[166:169], v[186:189], v[52:55]
	v_mfma_f32_16x16x32_bf16 v[48:51], v[178:181], v[186:189], v[48:51]
	v_mfma_f32_16x16x32_bf16 v[36:39], v[166:169], v[194:197], v[36:39]
	v_mfma_f32_16x16x32_bf16 v[32:35], v[178:181], v[194:197], v[32:35]
	v_mfma_f32_16x16x32_bf16 v[20:23], v[166:169], v[202:205], v[20:23]
	v_mfma_f32_16x16x32_bf16 v[16:19], v[178:181], v[202:205], v[16:19]
	v_mfma_f32_16x16x32_bf16 v[4:7], v[166:169], v[210:213], v[4:7]
	v_mfma_f32_16x16x32_bf16 v[0:3], v[178:181], v[210:213], v[0:3]
	v_mfma_f32_16x16x32_bf16 v[52:55], v[170:173], v[190:193], v[52:55]
	v_mfma_f32_16x16x32_bf16 v[48:51], v[182:185], v[190:193], v[48:51]
	v_mfma_f32_16x16x32_bf16 v[36:39], v[170:173], v[198:201], v[36:39]
	v_mfma_f32_16x16x32_bf16 v[32:35], v[182:185], v[198:201], v[32:35]
	v_mfma_f32_16x16x32_bf16 v[20:23], v[170:173], v[206:209], v[20:23]
	v_mfma_f32_16x16x32_bf16 v[16:19], v[182:185], v[206:209], v[16:19]
	v_mfma_f32_16x16x32_bf16 v[4:7], v[170:173], v[214:217], v[4:7]
	v_mfma_f32_16x16x32_bf16 v[0:3], v[182:185], v[214:217], v[0:3]
	s_setprio 0
	s_barrier
	s_add_i32 s69, 0, 0x18000
	s_add_i32 s70, 0, 0x1c000
	v_add_u32_e32 v162, s69, v148
	v_add_u32_e32 v182, s70, v148
	ds_read_b128 v[144:147], v162
	ds_read_b128 v[154:157], v162 offset:1024
	ds_read_b128 v[158:161], v162 offset:2048
	ds_read_b128 v[162:165], v162 offset:3072
	ds_read_b128 v[166:169], v182
	ds_read_b128 v[170:173], v182 offset:1024
	ds_read_b128 v[178:181], v182 offset:2048
	ds_read_b128 v[182:185], v182 offset:3072
	s_add_u32 s48, s54, 0x200000
	s_addc_u32 s49, s55, 0
	s_mov_b32 m0, s47
	v_lshl_add_u64 v[224:225], s[48:49], 0, v[128:129]
	ds_read_b128 v[186:189], v153 offset:32768
	ds_read_b128 v[190:193], v153 offset:33792
	ds_read_b128 v[194:197], v153 offset:34816
	ds_read_b128 v[198:201], v153 offset:35840
	ds_read_b128 v[202:205], v153 offset:36864
	ds_read_b128 v[206:209], v153 offset:37888
	ds_read_b128 v[210:213], v153 offset:38912
	ds_read_b128 v[214:217], v153 offset:39936
	global_load_lds_dwordx4 v[224:225], off
	v_lshl_add_u64 v[224:225], s[48:49], 0, v[132:133]
	s_mov_b32 m0, s56
	s_nop 0
	global_load_lds_dwordx4 v[224:225], off
	s_waitcnt vmcnt(8)
	s_waitcnt lgkmcnt(0)
	s_barrier
	s_setprio 1
	s_waitcnt lgkmcnt(0)
	v_mfma_f32_16x16x32_bf16 v[124:127], v[144:147], v[186:189], v[124:127]
	v_mfma_f32_16x16x32_bf16 v[120:123], v[158:161], v[186:189], v[120:123]
	v_mfma_f32_16x16x32_bf16 v[108:111], v[144:147], v[194:197], v[108:111]
	v_mfma_f32_16x16x32_bf16 v[104:107], v[158:161], v[194:197], v[104:107]
	v_mfma_f32_16x16x32_bf16 v[92:95], v[144:147], v[202:205], v[92:95]
	v_mfma_f32_16x16x32_bf16 v[88:91], v[158:161], v[202:205], v[88:91]
	v_mfma_f32_16x16x32_bf16 v[76:79], v[144:147], v[210:213], v[76:79]
	v_mfma_f32_16x16x32_bf16 v[72:75], v[158:161], v[210:213], v[72:75]
	v_mfma_f32_16x16x32_bf16 v[124:127], v[154:157], v[190:193], v[124:127]
	v_mfma_f32_16x16x32_bf16 v[120:123], v[162:165], v[190:193], v[120:123]
	v_mfma_f32_16x16x32_bf16 v[108:111], v[154:157], v[198:201], v[108:111]
	v_mfma_f32_16x16x32_bf16 v[104:107], v[162:165], v[198:201], v[104:107]
	v_mfma_f32_16x16x32_bf16 v[92:95], v[154:157], v[206:209], v[92:95]
	v_mfma_f32_16x16x32_bf16 v[88:91], v[162:165], v[206:209], v[88:91]
	v_mfma_f32_16x16x32_bf16 v[76:79], v[154:157], v[214:217], v[76:79]
	v_mfma_f32_16x16x32_bf16 v[72:75], v[162:165], v[214:217], v[72:75]
	v_mfma_f32_16x16x32_bf16 v[116:119], v[166:169], v[186:189], v[116:119]
	v_mfma_f32_16x16x32_bf16 v[112:115], v[178:181], v[186:189], v[112:115]
	v_mfma_f32_16x16x32_bf16 v[100:103], v[166:169], v[194:197], v[100:103]
	v_mfma_f32_16x16x32_bf16 v[96:99], v[178:181], v[194:197], v[96:99]
	v_mfma_f32_16x16x32_bf16 v[84:87], v[166:169], v[202:205], v[84:87]
	v_mfma_f32_16x16x32_bf16 v[80:83], v[178:181], v[202:205], v[80:83]
	v_mfma_f32_16x16x32_bf16 v[68:71], v[166:169], v[210:213], v[68:71]
	v_mfma_f32_16x16x32_bf16 v[64:67], v[178:181], v[210:213], v[64:67]
	v_mfma_f32_16x16x32_bf16 v[116:119], v[170:173], v[190:193], v[116:119]
	v_mfma_f32_16x16x32_bf16 v[112:115], v[182:185], v[190:193], v[112:115]
	v_mfma_f32_16x16x32_bf16 v[100:103], v[170:173], v[198:201], v[100:103]
	v_mfma_f32_16x16x32_bf16 v[96:99], v[182:185], v[198:201], v[96:99]
	v_mfma_f32_16x16x32_bf16 v[84:87], v[170:173], v[206:209], v[84:87]
	v_mfma_f32_16x16x32_bf16 v[80:83], v[182:185], v[206:209], v[80:83]
	v_mfma_f32_16x16x32_bf16 v[68:71], v[170:173], v[214:217], v[68:71]
	v_mfma_f32_16x16x32_bf16 v[64:67], v[182:185], v[214:217], v[64:67]
	s_setprio 0
	s_barrier
	s_add_i32 s48, s69, s88
	v_lshl_add_u64 v[174:175], v[174:175], 0, s[16:17]
	s_mov_b32 m0, s48
	ds_read_b128 v[186:189], v153 offset:49152
	ds_read_b128 v[190:193], v153 offset:50176
	ds_read_b128 v[194:197], v153 offset:51200
	ds_read_b128 v[198:201], v153 offset:52224
	ds_read_b128 v[202:205], v153 offset:53248
	ds_read_b128 v[206:209], v153 offset:54272
	ds_read_b128 v[210:213], v153 offset:55296
	ds_read_b128 v[214:217], v153 offset:56320
	global_load_lds_dwordx4 v[174:175], off
	s_add_i32 m0, s48, 0x2000
	s_add_u32 s48, s52, 0x200080
	v_lshl_add_u64 v[174:175], v[218:219], 0, s[16:17]
	s_addc_u32 s49, s53, 0
	s_add_i32 s52, s70, s88
	global_load_lds_dwordx4 v[174:175], off
	v_lshl_add_u64 v[174:175], s[48:49], 0, v[130:131]
	s_mov_b32 m0, s52
	s_nop 0
	global_load_lds_dwordx4 v[174:175], off
	v_lshl_add_u64 v[174:175], s[48:49], 0, v[134:135]
	s_add_i32 m0, s52, 0x2000
	s_nop 0
	global_load_lds_dwordx4 v[174:175], off
	v_lshl_add_u64 v[174:175], v[220:221], 0, s[16:17]
	s_mov_b32 m0, s58
	s_nop 0
	global_load_lds_dwordx4 v[174:175], off
	v_lshl_add_u64 v[174:175], v[222:223], 0, s[16:17]
	s_mov_b32 m0, s59
	s_nop 0
	global_load_lds_dwordx4 v[174:175], off
	s_waitcnt vmcnt(8)
	s_waitcnt lgkmcnt(0)
	s_barrier
	s_setprio 1
	s_waitcnt lgkmcnt(0)
	v_mfma_f32_16x16x32_bf16 v[60:63], v[144:147], v[186:189], v[60:63]
	v_mfma_f32_16x16x32_bf16 v[56:59], v[158:161], v[186:189], v[56:59]
	v_mfma_f32_16x16x32_bf16 v[44:47], v[144:147], v[194:197], v[44:47]
	v_mfma_f32_16x16x32_bf16 v[40:43], v[158:161], v[194:197], v[40:43]
	v_mfma_f32_16x16x32_bf16 v[28:31], v[144:147], v[202:205], v[28:31]
	v_mfma_f32_16x16x32_bf16 v[24:27], v[158:161], v[202:205], v[24:27]
	v_mfma_f32_16x16x32_bf16 v[12:15], v[144:147], v[210:213], v[12:15]
	v_mfma_f32_16x16x32_bf16 v[8:11], v[158:161], v[210:213], v[8:11]
	v_mfma_f32_16x16x32_bf16 v[60:63], v[154:157], v[190:193], v[60:63]
	v_mfma_f32_16x16x32_bf16 v[56:59], v[162:165], v[190:193], v[56:59]
	v_mfma_f32_16x16x32_bf16 v[44:47], v[154:157], v[198:201], v[44:47]
	v_mfma_f32_16x16x32_bf16 v[40:43], v[162:165], v[198:201], v[40:43]
	v_mfma_f32_16x16x32_bf16 v[28:31], v[154:157], v[206:209], v[28:31]
	v_mfma_f32_16x16x32_bf16 v[24:27], v[162:165], v[206:209], v[24:27]
	v_mfma_f32_16x16x32_bf16 v[12:15], v[154:157], v[214:217], v[12:15]
	v_mfma_f32_16x16x32_bf16 v[8:11], v[162:165], v[214:217], v[8:11]
	v_mfma_f32_16x16x32_bf16 v[52:55], v[166:169], v[186:189], v[52:55]
	v_mfma_f32_16x16x32_bf16 v[48:51], v[178:181], v[186:189], v[48:51]
	v_mfma_f32_16x16x32_bf16 v[36:39], v[166:169], v[194:197], v[36:39]
	v_mfma_f32_16x16x32_bf16 v[32:35], v[178:181], v[194:197], v[32:35]
	v_mfma_f32_16x16x32_bf16 v[20:23], v[166:169], v[202:205], v[20:23]
	v_mfma_f32_16x16x32_bf16 v[16:19], v[178:181], v[202:205], v[16:19]
	v_mfma_f32_16x16x32_bf16 v[4:7], v[166:169], v[210:213], v[4:7]
	v_mfma_f32_16x16x32_bf16 v[0:3], v[178:181], v[210:213], v[0:3]
	v_mfma_f32_16x16x32_bf16 v[52:55], v[170:173], v[190:193], v[52:55]
	v_mfma_f32_16x16x32_bf16 v[48:51], v[182:185], v[190:193], v[48:51]
	v_mfma_f32_16x16x32_bf16 v[36:39], v[170:173], v[198:201], v[36:39]
	v_mfma_f32_16x16x32_bf16 v[32:35], v[182:185], v[198:201], v[32:35]
	v_mfma_f32_16x16x32_bf16 v[20:23], v[170:173], v[206:209], v[20:23]
	v_mfma_f32_16x16x32_bf16 v[16:19], v[182:185], v[206:209], v[16:19]
	v_mfma_f32_16x16x32_bf16 v[4:7], v[170:173], v[214:217], v[4:7]
	v_mfma_f32_16x16x32_bf16 v[0:3], v[182:185], v[214:217], v[0:3]
	s_setprio 0
	s_barrier
	s_add_i32 s68, s68, 2
	s_add_u32 s66, s66, 0x100
	s_addc_u32 s67, s67, 0
	s_cmpk_gt_u32 s68, 0x7d
	s_mov_b64 s[48:49], s[50:51]
	s_cbranch_scc0 .LBB0_1599
	s_and_b64 vcc, exec, s[10:11]
	s_cbranch_vccz .LBB0_1602
	s_barrier
